# MERGE phase software-pipelined: next item's LSE/OG loads issued before the current item is computed (unrolled 16 items, two register sets)
# baseline (speedup 1.0000x reference)
; DI float lo_f(unsigned u) { return __uint_as_float(u << 16); }
; DI float hi_f(unsigned u) { return __uint_as_float(u & 0xffff0000u); }
; DI unsigned pk2(float lo, float hi) { return pg8::cvt_pk_bf16(lo, hi); }
; __global__ void __launch_bounds__(512, 2) fwd_mega(Args a) {
;     ...
;         for (int i = bx * 512 + tid; i < TH * 64; i += G * 512) {
;             const int tok = i >> 6, rem = i & 63, hs = rem >> 4, ch = rem & 15;
;             const float l0 = LSE[tok * 12 + hs], l1 = LSE[tok * 12 + 4 + hs], l2 = LSE[tok * 12 + 8 + hs];
;             const float mx = fmaxf(l0, fmaxf(l1, l2)); float w0 = __expf(l0 - mx), w1 = __expf(l1 - mx), w2 = __expf(l2 - mx); const float inv = 1.0f / (w0 + w1 + w2); w0 *= inv; w1 *= inv; w2 *= inv;
;             const size_t off = (size_t)tok * 512 + hs * 128 + ch * 8;
;             const v4u o0 = *(const v4u*)(OG + off), o1 = *(const v4u*)(OG + (size_t)TH * 512 + off), o2 = *(const v4u*)(OG + (size_t)2 * TH * 512 + off);
;             v4u r;
;             r.x = pk2(w0 * lo_f(o0.x) + w1 * lo_f(o1.x) + w2 * lo_f(o2.x), w0 * hi_f(o0.x) + w1 * hi_f(o1.x) + w2 * hi_f(o2.x));
;             r.y = pk2(w0 * lo_f(o0.y) + w1 * lo_f(o1.y) + w2 * lo_f(o2.y), w0 * hi_f(o0.y) + w1 * hi_f(o1.y) + w2 * hi_f(o2.y));
;             r.z = pk2(w0 * lo_f(o0.z) + w1 * lo_f(o1.z) + w2 * lo_f(o2.z), w0 * hi_f(o0.z) + w1 * hi_f(o1.z) + w2 * hi_f(o2.z));
;             r.w = pk2(w0 * lo_f(o0.w) + w1 * lo_f(o1.w) + w2 * lo_f(o2.w), w0 * hi_f(o0.w) + w1 * hi_f(o1.w) + w2 * hi_f(o2.w));
;             *(v4u*)(ATT + off) = r;
;         } }
.LBB0_491:
	s_or_b64 exec, exec, s[0:1]
	s_waitcnt lgkmcnt(0)
	v_mov_b32_e32 v2, v188
	v_readlane_b32 s0, v252, 28
	s_barrier
	s_nop 0
	v_add_u32_e32 v0, s0, v2
	s_mov_b32 s0, 0x200000
	v_cmp_gt_i32_e32 vcc, s0, v0
	s_and_saveexec_b64 s[0:1], vcc
	v_readlane_b32 s6, v253, 49
	s_cbranch_execz .LBB0_494
	v_lshlrev_b32_e32 v2, 3, v2
	v_ashrrev_i32_e32 v4, 6, v0
	v_bfe_u32 v3, v0, 4, 2
	v_mul_lo_u32 v5, v4, 12
	v_or_b32_e32 v6, v5, v3
	v_ashrrev_i32_e32 v7, 31, v6
	v_lshl_add_u64 v[6:7], v[6:7], 2, s[90:91]
	v_lshlrev_b32_e32 v3, 7, v3
	v_mov_b32_e32 v48, v4
	v_ashrrev_i32_e32 v49, 31, v4
	v_lshlrev_b64 v[48:49], 9, v[48:49]
	v_and_b32_e32 v50, 0x78, v2
	v_or3_b32 v48, v48, v3, v50
	v_lshlrev_b64 v[48:49], 1, v[48:49]
	v_lshl_add_u64 v[8:9], s[88:89], 0, v[48:49]
	v_lshl_add_u64 v[10:11], s[30:31], 0, v[48:49]
	v_lshl_add_u64 v[12:13], s[48:49], 0, v[48:49]
	v_lshl_add_u64 v[14:15], s[92:93], 0, v[48:49]
	s_mov_b64 s[98:99], 0x18000
	s_mov_b64 s[100:101], 0x200000
	global_load_dword v16, v[6:7], off
	global_load_dword v17, v[6:7], off offset:16
	global_load_dword v18, v[6:7], off offset:32
	global_load_dwordx4 v[20:23], v[8:9], off
	global_load_dwordx4 v[24:27], v[10:11], off
	global_load_dwordx4 v[28:31], v[12:13], off
	v_lshl_add_u64 v[6:7], v[6:7], 0, s[98:99]
	v_lshl_add_u64 v[8:9], v[8:9], 0, s[100:101]
	v_lshl_add_u64 v[10:11], v[10:11], 0, s[100:101]
	v_lshl_add_u64 v[12:13], v[12:13], 0, s[100:101]
	global_load_dword v32, v[6:7], off
	global_load_dword v33, v[6:7], off offset:16
	global_load_dword v34, v[6:7], off offset:32
	global_load_dwordx4 v[36:39], v[8:9], off
	global_load_dwordx4 v[40:43], v[10:11], off
	global_load_dwordx4 v[44:47], v[12:13], off
	v_lshl_add_u64 v[6:7], v[6:7], 0, s[98:99]
	v_lshl_add_u64 v[8:9], v[8:9], 0, s[100:101]
	v_lshl_add_u64 v[10:11], v[10:11], 0, s[100:101]
	v_lshl_add_u64 v[12:13], v[12:13], 0, s[100:101]
	s_waitcnt vmcnt(6)
	v_max3_f32 v48, v16, v17, v18
	v_sub_f32_e32 v49, v16, v48
	v_mul_f32_e32 v49, 0x3fb8aa3b, v49
	v_exp_f32_e32 v49, v49
	v_sub_f32_e32 v50, v17, v48
	v_mul_f32_e32 v50, 0x3fb8aa3b, v50
	v_sub_f32_e32 v51, v18, v48
	v_exp_f32_e32 v50, v50
	v_mul_f32_e32 v51, 0x3fb8aa3b, v51
	v_exp_f32_e32 v51, v51
	v_add_f32_e32 v52, v49, v50
	v_add_f32_e32 v52, v51, v52
	v_div_scale_f32 v53, s[4:5], v52, v52, 1.0
	v_rcp_f32_e32 v54, v53
	s_nop 0
	v_fma_f32 v55, -v53, v54, 1.0
	v_fmac_f32_e32 v54, v55, v54
	v_div_scale_f32 v55, vcc, 1.0, v52, 1.0
	v_mul_f32_e32 v59, v55, v54
	v_fma_f32 v60, -v53, v59, v55
	v_fmac_f32_e32 v59, v60, v54
	v_fma_f32 v53, -v53, v59, v55
	v_div_fmas_f32 v53, v53, v54, v59
	v_div_fixup_f32 v53, v53, v52, 1.0
	v_mul_f32_e32 v57, v50, v53
	v_mul_f32_e32 v58, v51, v53
	v_mul_f32_e32 v56, v49, v53
	v_lshlrev_b32_e32 v48, 16, v20
	v_lshlrev_b32_e32 v49, 16, v24
	v_lshlrev_b32_e32 v50, 16, v28
	v_mul_f32_e32 v48, v56, v48
	v_mul_f32_e32 v50, v58, v50
	v_fma_f32 v59, v57, v49, v48
	v_add_f32_e32 v59, v50, v59
	v_and_b32_e32 v48, 0xffff0000, v20
	v_and_b32_e32 v49, 0xffff0000, v24
	v_and_b32_e32 v50, 0xffff0000, v28
	v_mul_f32_e32 v48, v56, v48
	v_mul_f32_e32 v50, v58, v50
	v_fma_f32 v60, v57, v49, v48
	v_add_f32_e32 v60, v50, v60
	v_cvt_pk_bf16_f32 v52, v59, v60
	v_lshlrev_b32_e32 v48, 16, v21
	v_lshlrev_b32_e32 v49, 16, v25
	v_lshlrev_b32_e32 v50, 16, v29
	v_mul_f32_e32 v48, v56, v48
	v_mul_f32_e32 v50, v58, v50
	v_fma_f32 v59, v57, v49, v48
	v_add_f32_e32 v59, v50, v59
	v_and_b32_e32 v48, 0xffff0000, v21
	v_and_b32_e32 v49, 0xffff0000, v25
	v_and_b32_e32 v50, 0xffff0000, v29
	v_mul_f32_e32 v48, v56, v48
	v_mul_f32_e32 v50, v58, v50
	v_fma_f32 v60, v57, v49, v48
	v_add_f32_e32 v60, v50, v60
	v_cvt_pk_bf16_f32 v53, v59, v60
	v_lshlrev_b32_e32 v48, 16, v22
	v_lshlrev_b32_e32 v49, 16, v26
	v_lshlrev_b32_e32 v50, 16, v30
	v_mul_f32_e32 v48, v56, v48
	v_mul_f32_e32 v50, v58, v50
	v_fma_f32 v59, v57, v49, v48
	v_add_f32_e32 v59, v50, v59
	v_and_b32_e32 v48, 0xffff0000, v22
	v_and_b32_e32 v49, 0xffff0000, v26
	v_and_b32_e32 v50, 0xffff0000, v30
	v_mul_f32_e32 v48, v56, v48
	v_mul_f32_e32 v50, v58, v50
	v_fma_f32 v60, v57, v49, v48
	v_add_f32_e32 v60, v50, v60
	v_cvt_pk_bf16_f32 v54, v59, v60
	v_lshlrev_b32_e32 v48, 16, v23
	v_lshlrev_b32_e32 v49, 16, v27
	v_lshlrev_b32_e32 v50, 16, v31
	v_mul_f32_e32 v48, v56, v48
	v_mul_f32_e32 v50, v58, v50
	v_fma_f32 v59, v57, v49, v48
	v_add_f32_e32 v59, v50, v59
	v_and_b32_e32 v48, 0xffff0000, v23
	v_and_b32_e32 v49, 0xffff0000, v27
	v_and_b32_e32 v50, 0xffff0000, v31
	v_mul_f32_e32 v48, v56, v48
	v_mul_f32_e32 v50, v58, v50
	v_fma_f32 v60, v57, v49, v48
	v_add_f32_e32 v60, v50, v60
	v_cvt_pk_bf16_f32 v55, v59, v60
	global_store_dwordx4 v[14:15], v[52:55], off
	v_lshl_add_u64 v[14:15], v[14:15], 0, s[100:101]
	global_load_dword v16, v[6:7], off
	global_load_dword v17, v[6:7], off offset:16
	global_load_dword v18, v[6:7], off offset:32
	global_load_dwordx4 v[20:23], v[8:9], off
	global_load_dwordx4 v[24:27], v[10:11], off
	global_load_dwordx4 v[28:31], v[12:13], off
	v_lshl_add_u64 v[6:7], v[6:7], 0, s[98:99]
	v_lshl_add_u64 v[8:9], v[8:9], 0, s[100:101]
	v_lshl_add_u64 v[10:11], v[10:11], 0, s[100:101]
	v_lshl_add_u64 v[12:13], v[12:13], 0, s[100:101]
	s_waitcnt vmcnt(7)
; DI float lo_f(unsigned u) { return __uint_as_float(u << 16); }
; DI float hi_f(unsigned u) { return __uint_as_float(u & 0xffff0000u); }
; DI unsigned pk2(float lo, float hi) { return pg8::cvt_pk_bf16(lo, hi); }
; __global__ void __launch_bounds__(512, 2) fwd_mega(Args a) {
;     ...
;         for (int i = bx * 512 + tid; i < TH * 64; i += G * 512) {
;             const int tok = i >> 6, rem = i & 63, hs = rem >> 4, ch = rem & 15;
;             const float l0 = LSE[tok * 12 + hs], l1 = LSE[tok * 12 + 4 + hs], l2 = LSE[tok * 12 + 8 + hs];
;             const float mx = fmaxf(l0, fmaxf(l1, l2)); float w0 = __expf(l0 - mx), w1 = __expf(l1 - mx), w2 = __expf(l2 - mx); const float inv = 1.0f / (w0 + w1 + w2); w0 *= inv; w1 *= inv; w2 *= inv;
;             const size_t off = (size_t)tok * 512 + hs * 128 + ch * 8;
;             const v4u o0 = *(const v4u*)(OG + off), o1 = *(const v4u*)(OG + (size_t)TH * 512 + off), o2 = *(const v4u*)(OG + (size_t)2 * TH * 512 + off);
;             v4u r;
;             r.x = pk2(w0 * lo_f(o0.x) + w1 * lo_f(o1.x) + w2 * lo_f(o2.x), w0 * hi_f(o0.x) + w1 * hi_f(o1.x) + w2 * hi_f(o2.x));
;             r.y = pk2(w0 * lo_f(o0.y) + w1 * lo_f(o1.y) + w2 * lo_f(o2.y), w0 * hi_f(o0.y) + w1 * hi_f(o1.y) + w2 * hi_f(o2.y));
;             r.z = pk2(w0 * lo_f(o0.z) + w1 * lo_f(o1.z) + w2 * lo_f(o2.z), w0 * hi_f(o0.z) + w1 * hi_f(o1.z) + w2 * hi_f(o2.z));
;             r.w = pk2(w0 * lo_f(o0.w) + w1 * lo_f(o1.w) + w2 * lo_f(o2.w), w0 * hi_f(o0.w) + w1 * hi_f(o1.w) + w2 * hi_f(o2.w));
;             *(v4u*)(ATT + off) = r;
	v_max3_f32 v48, v32, v33, v34
	v_sub_f32_e32 v49, v32, v48
	v_mul_f32_e32 v49, 0x3fb8aa3b, v49
	v_exp_f32_e32 v49, v49
	v_sub_f32_e32 v50, v33, v48
	v_mul_f32_e32 v50, 0x3fb8aa3b, v50
	v_sub_f32_e32 v51, v34, v48
	v_exp_f32_e32 v50, v50
	v_mul_f32_e32 v51, 0x3fb8aa3b, v51
	v_exp_f32_e32 v51, v51
	v_add_f32_e32 v52, v49, v50
	v_add_f32_e32 v52, v51, v52
	v_div_scale_f32 v53, s[4:5], v52, v52, 1.0
	v_rcp_f32_e32 v54, v53
	s_nop 0
	v_fma_f32 v55, -v53, v54, 1.0
	v_fmac_f32_e32 v54, v55, v54
	v_div_scale_f32 v55, vcc, 1.0, v52, 1.0
	v_mul_f32_e32 v59, v55, v54
	v_fma_f32 v60, -v53, v59, v55
	v_fmac_f32_e32 v59, v60, v54
	v_fma_f32 v53, -v53, v59, v55
	v_div_fmas_f32 v53, v53, v54, v59
	v_div_fixup_f32 v53, v53, v52, 1.0
	v_mul_f32_e32 v57, v50, v53
	v_mul_f32_e32 v58, v51, v53
	v_mul_f32_e32 v56, v49, v53
	v_lshlrev_b32_e32 v48, 16, v36
	v_lshlrev_b32_e32 v49, 16, v40
	v_lshlrev_b32_e32 v50, 16, v44
	v_mul_f32_e32 v48, v56, v48
	v_mul_f32_e32 v50, v58, v50
	v_fma_f32 v59, v57, v49, v48
	v_add_f32_e32 v59, v50, v59
	v_and_b32_e32 v48, 0xffff0000, v36
	v_and_b32_e32 v49, 0xffff0000, v40
	v_and_b32_e32 v50, 0xffff0000, v44
	v_mul_f32_e32 v48, v56, v48
	v_mul_f32_e32 v50, v58, v50
	v_fma_f32 v60, v57, v49, v48
	v_add_f32_e32 v60, v50, v60
	v_cvt_pk_bf16_f32 v52, v59, v60
	v_lshlrev_b32_e32 v48, 16, v37
	v_lshlrev_b32_e32 v49, 16, v41
	v_lshlrev_b32_e32 v50, 16, v45
	v_mul_f32_e32 v48, v56, v48
	v_mul_f32_e32 v50, v58, v50
	v_fma_f32 v59, v57, v49, v48
	v_add_f32_e32 v59, v50, v59
	v_and_b32_e32 v48, 0xffff0000, v37
	v_and_b32_e32 v49, 0xffff0000, v41
	v_and_b32_e32 v50, 0xffff0000, v45
	v_mul_f32_e32 v48, v56, v48
	v_mul_f32_e32 v50, v58, v50
	v_fma_f32 v60, v57, v49, v48
	v_add_f32_e32 v60, v50, v60
	v_cvt_pk_bf16_f32 v53, v59, v60
	v_lshlrev_b32_e32 v48, 16, v38
	v_lshlrev_b32_e32 v49, 16, v42
	v_lshlrev_b32_e32 v50, 16, v46
	v_mul_f32_e32 v48, v56, v48
	v_mul_f32_e32 v50, v58, v50
	v_fma_f32 v59, v57, v49, v48
	v_add_f32_e32 v59, v50, v59
	v_and_b32_e32 v48, 0xffff0000, v38
	v_and_b32_e32 v49, 0xffff0000, v42
	v_and_b32_e32 v50, 0xffff0000, v46
	v_mul_f32_e32 v48, v56, v48
	v_mul_f32_e32 v50, v58, v50
	v_fma_f32 v60, v57, v49, v48
	v_add_f32_e32 v60, v50, v60
	v_cvt_pk_bf16_f32 v54, v59, v60
	v_lshlrev_b32_e32 v48, 16, v39
	v_lshlrev_b32_e32 v49, 16, v43
	v_lshlrev_b32_e32 v50, 16, v47
	v_mul_f32_e32 v48, v56, v48
	v_mul_f32_e32 v50, v58, v50
	v_fma_f32 v59, v57, v49, v48
	v_add_f32_e32 v59, v50, v59
	v_and_b32_e32 v48, 0xffff0000, v39
	v_and_b32_e32 v49, 0xffff0000, v43
	v_and_b32_e32 v50, 0xffff0000, v47
	v_mul_f32_e32 v48, v56, v48
	v_mul_f32_e32 v50, v58, v50
	v_fma_f32 v60, v57, v49, v48
	v_add_f32_e32 v60, v50, v60
	v_cvt_pk_bf16_f32 v55, v59, v60
	global_store_dwordx4 v[14:15], v[52:55], off
	v_lshl_add_u64 v[14:15], v[14:15], 0, s[100:101]
	global_load_dword v32, v[6:7], off
	global_load_dword v33, v[6:7], off offset:16
	global_load_dword v34, v[6:7], off offset:32
	global_load_dwordx4 v[36:39], v[8:9], off
	global_load_dwordx4 v[40:43], v[10:11], off
	global_load_dwordx4 v[44:47], v[12:13], off
	v_lshl_add_u64 v[6:7], v[6:7], 0, s[98:99]
	v_lshl_add_u64 v[8:9], v[8:9], 0, s[100:101]
	v_lshl_add_u64 v[10:11], v[10:11], 0, s[100:101]
	v_lshl_add_u64 v[12:13], v[12:13], 0, s[100:101]
	s_waitcnt vmcnt(7)
	v_max3_f32 v48, v16, v17, v18
	v_sub_f32_e32 v49, v16, v48
	v_mul_f32_e32 v49, 0x3fb8aa3b, v49
	v_exp_f32_e32 v49, v49
	v_sub_f32_e32 v50, v17, v48
	v_mul_f32_e32 v50, 0x3fb8aa3b, v50
	v_sub_f32_e32 v51, v18, v48
	v_exp_f32_e32 v50, v50
	v_mul_f32_e32 v51, 0x3fb8aa3b, v51
	v_exp_f32_e32 v51, v51
	v_add_f32_e32 v52, v49, v50
	v_add_f32_e32 v52, v51, v52
	v_div_scale_f32 v53, s[4:5], v52, v52, 1.0
	v_rcp_f32_e32 v54, v53
	s_nop 0
	v_fma_f32 v55, -v53, v54, 1.0
	v_fmac_f32_e32 v54, v55, v54
	v_div_scale_f32 v55, vcc, 1.0, v52, 1.0
	v_mul_f32_e32 v59, v55, v54
	v_fma_f32 v60, -v53, v59, v55
	v_fmac_f32_e32 v59, v60, v54
	v_fma_f32 v53, -v53, v59, v55
	v_div_fmas_f32 v53, v53, v54, v59
	v_div_fixup_f32 v53, v53, v52, 1.0
	v_mul_f32_e32 v57, v50, v53
	v_mul_f32_e32 v58, v51, v53
	v_mul_f32_e32 v56, v49, v53
	v_lshlrev_b32_e32 v48, 16, v20
	v_lshlrev_b32_e32 v49, 16, v24
	v_lshlrev_b32_e32 v50, 16, v28
	v_mul_f32_e32 v48, v56, v48
	v_mul_f32_e32 v50, v58, v50
	v_fma_f32 v59, v57, v49, v48
	v_add_f32_e32 v59, v50, v59
	v_and_b32_e32 v48, 0xffff0000, v20
	v_and_b32_e32 v49, 0xffff0000, v24
	v_and_b32_e32 v50, 0xffff0000, v28
	v_mul_f32_e32 v48, v56, v48
	v_mul_f32_e32 v50, v58, v50
	v_fma_f32 v60, v57, v49, v48
	v_add_f32_e32 v60, v50, v60
	v_cvt_pk_bf16_f32 v52, v59, v60
	v_lshlrev_b32_e32 v48, 16, v21
	v_lshlrev_b32_e32 v49, 16, v25
	v_lshlrev_b32_e32 v50, 16, v29
	v_mul_f32_e32 v48, v56, v48
	v_mul_f32_e32 v50, v58, v50
	v_fma_f32 v59, v57, v49, v48
	v_add_f32_e32 v59, v50, v59
	v_and_b32_e32 v48, 0xffff0000, v21
	v_and_b32_e32 v49, 0xffff0000, v25
	v_and_b32_e32 v50, 0xffff0000, v29
	v_mul_f32_e32 v48, v56, v48
	v_mul_f32_e32 v50, v58, v50
	v_fma_f32 v60, v57, v49, v48
	v_add_f32_e32 v60, v50, v60
	v_cvt_pk_bf16_f32 v53, v59, v60
	v_lshlrev_b32_e32 v48, 16, v22
	v_lshlrev_b32_e32 v49, 16, v26
	v_lshlrev_b32_e32 v50, 16, v30
	v_mul_f32_e32 v48, v56, v48
	v_mul_f32_e32 v50, v58, v50
	v_fma_f32 v59, v57, v49, v48
	v_add_f32_e32 v59, v50, v59
	v_and_b32_e32 v48, 0xffff0000, v22
	v_and_b32_e32 v49, 0xffff0000, v26
	v_and_b32_e32 v50, 0xffff0000, v30
	v_mul_f32_e32 v48, v56, v48
	v_mul_f32_e32 v50, v58, v50
	v_fma_f32 v60, v57, v49, v48
	v_add_f32_e32 v60, v50, v60
	v_cvt_pk_bf16_f32 v54, v59, v60
	v_lshlrev_b32_e32 v48, 16, v23
	v_lshlrev_b32_e32 v49, 16, v27
	v_lshlrev_b32_e32 v50, 16, v31
	v_mul_f32_e32 v48, v56, v48
	v_mul_f32_e32 v50, v58, v50
	v_fma_f32 v59, v57, v49, v48
	v_add_f32_e32 v59, v50, v59
	v_and_b32_e32 v48, 0xffff0000, v23
	v_and_b32_e32 v49, 0xffff0000, v27
	v_and_b32_e32 v50, 0xffff0000, v31
	v_mul_f32_e32 v48, v56, v48
	v_mul_f32_e32 v50, v58, v50
	v_fma_f32 v60, v57, v49, v48
	v_add_f32_e32 v60, v50, v60
	v_cvt_pk_bf16_f32 v55, v59, v60
	global_store_dwordx4 v[14:15], v[52:55], off
	v_lshl_add_u64 v[14:15], v[14:15], 0, s[100:101]
	global_load_dword v16, v[6:7], off
	global_load_dword v17, v[6:7], off offset:16
	global_load_dword v18, v[6:7], off offset:32
	global_load_dwordx4 v[20:23], v[8:9], off
	global_load_dwordx4 v[24:27], v[10:11], off
	global_load_dwordx4 v[28:31], v[12:13], off
	v_lshl_add_u64 v[6:7], v[6:7], 0, s[98:99]
	v_lshl_add_u64 v[8:9], v[8:9], 0, s[100:101]
	v_lshl_add_u64 v[10:11], v[10:11], 0, s[100:101]
	v_lshl_add_u64 v[12:13], v[12:13], 0, s[100:101]
	s_waitcnt vmcnt(7)
; DI float lo_f(unsigned u) { return __uint_as_float(u << 16); }
; DI float hi_f(unsigned u) { return __uint_as_float(u & 0xffff0000u); }
; DI unsigned pk2(float lo, float hi) { return pg8::cvt_pk_bf16(lo, hi); }
; __global__ void __launch_bounds__(512, 2) fwd_mega(Args a) {
;     ...
;         for (int i = bx * 512 + tid; i < TH * 64; i += G * 512) {
;             const int tok = i >> 6, rem = i & 63, hs = rem >> 4, ch = rem & 15;
;             const float l0 = LSE[tok * 12 + hs], l1 = LSE[tok * 12 + 4 + hs], l2 = LSE[tok * 12 + 8 + hs];
;             const float mx = fmaxf(l0, fmaxf(l1, l2)); float w0 = __expf(l0 - mx), w1 = __expf(l1 - mx), w2 = __expf(l2 - mx); const float inv = 1.0f / (w0 + w1 + w2); w0 *= inv; w1 *= inv; w2 *= inv;
;             const size_t off = (size_t)tok * 512 + hs * 128 + ch * 8;
;             const v4u o0 = *(const v4u*)(OG + off), o1 = *(const v4u*)(OG + (size_t)TH * 512 + off), o2 = *(const v4u*)(OG + (size_t)2 * TH * 512 + off);
;             v4u r;
;             r.x = pk2(w0 * lo_f(o0.x) + w1 * lo_f(o1.x) + w2 * lo_f(o2.x), w0 * hi_f(o0.x) + w1 * hi_f(o1.x) + w2 * hi_f(o2.x));
;             r.y = pk2(w0 * lo_f(o0.y) + w1 * lo_f(o1.y) + w2 * lo_f(o2.y), w0 * hi_f(o0.y) + w1 * hi_f(o1.y) + w2 * hi_f(o2.y));
;             r.z = pk2(w0 * lo_f(o0.z) + w1 * lo_f(o1.z) + w2 * lo_f(o2.z), w0 * hi_f(o0.z) + w1 * hi_f(o1.z) + w2 * hi_f(o2.z));
;             r.w = pk2(w0 * lo_f(o0.w) + w1 * lo_f(o1.w) + w2 * lo_f(o2.w), w0 * hi_f(o0.w) + w1 * hi_f(o1.w) + w2 * hi_f(o2.w));
;             *(v4u*)(ATT + off) = r;
	v_max3_f32 v48, v32, v33, v34
	v_sub_f32_e32 v49, v32, v48
	v_mul_f32_e32 v49, 0x3fb8aa3b, v49
	v_exp_f32_e32 v49, v49
	v_sub_f32_e32 v50, v33, v48
	v_mul_f32_e32 v50, 0x3fb8aa3b, v50
	v_sub_f32_e32 v51, v34, v48
	v_exp_f32_e32 v50, v50
	v_mul_f32_e32 v51, 0x3fb8aa3b, v51
	v_exp_f32_e32 v51, v51
	v_add_f32_e32 v52, v49, v50
	v_add_f32_e32 v52, v51, v52
	v_div_scale_f32 v53, s[4:5], v52, v52, 1.0
	v_rcp_f32_e32 v54, v53
	s_nop 0
	v_fma_f32 v55, -v53, v54, 1.0
	v_fmac_f32_e32 v54, v55, v54
	v_div_scale_f32 v55, vcc, 1.0, v52, 1.0
	v_mul_f32_e32 v59, v55, v54
	v_fma_f32 v60, -v53, v59, v55
	v_fmac_f32_e32 v59, v60, v54
	v_fma_f32 v53, -v53, v59, v55
	v_div_fmas_f32 v53, v53, v54, v59
	v_div_fixup_f32 v53, v53, v52, 1.0
	v_mul_f32_e32 v57, v50, v53
	v_mul_f32_e32 v58, v51, v53
	v_mul_f32_e32 v56, v49, v53
	v_lshlrev_b32_e32 v48, 16, v36
	v_lshlrev_b32_e32 v49, 16, v40
	v_lshlrev_b32_e32 v50, 16, v44
	v_mul_f32_e32 v48, v56, v48
	v_mul_f32_e32 v50, v58, v50
	v_fma_f32 v59, v57, v49, v48
	v_add_f32_e32 v59, v50, v59
	v_and_b32_e32 v48, 0xffff0000, v36
	v_and_b32_e32 v49, 0xffff0000, v40
	v_and_b32_e32 v50, 0xffff0000, v44
	v_mul_f32_e32 v48, v56, v48
	v_mul_f32_e32 v50, v58, v50
	v_fma_f32 v60, v57, v49, v48
	v_add_f32_e32 v60, v50, v60
	v_cvt_pk_bf16_f32 v52, v59, v60
	v_lshlrev_b32_e32 v48, 16, v37
	v_lshlrev_b32_e32 v49, 16, v41
	v_lshlrev_b32_e32 v50, 16, v45
	v_mul_f32_e32 v48, v56, v48
	v_mul_f32_e32 v50, v58, v50
	v_fma_f32 v59, v57, v49, v48
	v_add_f32_e32 v59, v50, v59
	v_and_b32_e32 v48, 0xffff0000, v37
	v_and_b32_e32 v49, 0xffff0000, v41
	v_and_b32_e32 v50, 0xffff0000, v45
	v_mul_f32_e32 v48, v56, v48
	v_mul_f32_e32 v50, v58, v50
	v_fma_f32 v60, v57, v49, v48
	v_add_f32_e32 v60, v50, v60
	v_cvt_pk_bf16_f32 v53, v59, v60
	v_lshlrev_b32_e32 v48, 16, v38
	v_lshlrev_b32_e32 v49, 16, v42
	v_lshlrev_b32_e32 v50, 16, v46
	v_mul_f32_e32 v48, v56, v48
	v_mul_f32_e32 v50, v58, v50
	v_fma_f32 v59, v57, v49, v48
	v_add_f32_e32 v59, v50, v59
	v_and_b32_e32 v48, 0xffff0000, v38
	v_and_b32_e32 v49, 0xffff0000, v42
	v_and_b32_e32 v50, 0xffff0000, v46
	v_mul_f32_e32 v48, v56, v48
	v_mul_f32_e32 v50, v58, v50
	v_fma_f32 v60, v57, v49, v48
	v_add_f32_e32 v60, v50, v60
	v_cvt_pk_bf16_f32 v54, v59, v60
	v_lshlrev_b32_e32 v48, 16, v39
	v_lshlrev_b32_e32 v49, 16, v43
	v_lshlrev_b32_e32 v50, 16, v47
	v_mul_f32_e32 v48, v56, v48
	v_mul_f32_e32 v50, v58, v50
	v_fma_f32 v59, v57, v49, v48
	v_add_f32_e32 v59, v50, v59
	v_and_b32_e32 v48, 0xffff0000, v39
	v_and_b32_e32 v49, 0xffff0000, v43
	v_and_b32_e32 v50, 0xffff0000, v47
	v_mul_f32_e32 v48, v56, v48
	v_mul_f32_e32 v50, v58, v50
	v_fma_f32 v60, v57, v49, v48
	v_add_f32_e32 v60, v50, v60
	v_cvt_pk_bf16_f32 v55, v59, v60
	global_store_dwordx4 v[14:15], v[52:55], off
	v_lshl_add_u64 v[14:15], v[14:15], 0, s[100:101]
	global_load_dword v32, v[6:7], off
	global_load_dword v33, v[6:7], off offset:16
	global_load_dword v34, v[6:7], off offset:32
	global_load_dwordx4 v[36:39], v[8:9], off
	global_load_dwordx4 v[40:43], v[10:11], off
	global_load_dwordx4 v[44:47], v[12:13], off
	v_lshl_add_u64 v[6:7], v[6:7], 0, s[98:99]
	v_lshl_add_u64 v[8:9], v[8:9], 0, s[100:101]
	v_lshl_add_u64 v[10:11], v[10:11], 0, s[100:101]
	v_lshl_add_u64 v[12:13], v[12:13], 0, s[100:101]
	s_waitcnt vmcnt(7)
	v_max3_f32 v48, v16, v17, v18
	v_sub_f32_e32 v49, v16, v48
	v_mul_f32_e32 v49, 0x3fb8aa3b, v49
	v_exp_f32_e32 v49, v49
	v_sub_f32_e32 v50, v17, v48
	v_mul_f32_e32 v50, 0x3fb8aa3b, v50
	v_sub_f32_e32 v51, v18, v48
	v_exp_f32_e32 v50, v50
	v_mul_f32_e32 v51, 0x3fb8aa3b, v51
	v_exp_f32_e32 v51, v51
	v_add_f32_e32 v52, v49, v50
	v_add_f32_e32 v52, v51, v52
	v_div_scale_f32 v53, s[4:5], v52, v52, 1.0
	v_rcp_f32_e32 v54, v53
	s_nop 0
	v_fma_f32 v55, -v53, v54, 1.0
	v_fmac_f32_e32 v54, v55, v54
	v_div_scale_f32 v55, vcc, 1.0, v52, 1.0
	v_mul_f32_e32 v59, v55, v54
	v_fma_f32 v60, -v53, v59, v55
	v_fmac_f32_e32 v59, v60, v54
	v_fma_f32 v53, -v53, v59, v55
	v_div_fmas_f32 v53, v53, v54, v59
	v_div_fixup_f32 v53, v53, v52, 1.0
	v_mul_f32_e32 v57, v50, v53
	v_mul_f32_e32 v58, v51, v53
	v_mul_f32_e32 v56, v49, v53
	v_lshlrev_b32_e32 v48, 16, v20
	v_lshlrev_b32_e32 v49, 16, v24
	v_lshlrev_b32_e32 v50, 16, v28
	v_mul_f32_e32 v48, v56, v48
	v_mul_f32_e32 v50, v58, v50
	v_fma_f32 v59, v57, v49, v48
	v_add_f32_e32 v59, v50, v59
	v_and_b32_e32 v48, 0xffff0000, v20
	v_and_b32_e32 v49, 0xffff0000, v24
	v_and_b32_e32 v50, 0xffff0000, v28
	v_mul_f32_e32 v48, v56, v48
	v_mul_f32_e32 v50, v58, v50
	v_fma_f32 v60, v57, v49, v48
	v_add_f32_e32 v60, v50, v60
	v_cvt_pk_bf16_f32 v52, v59, v60
	v_lshlrev_b32_e32 v48, 16, v21
	v_lshlrev_b32_e32 v49, 16, v25
	v_lshlrev_b32_e32 v50, 16, v29
	v_mul_f32_e32 v48, v56, v48
	v_mul_f32_e32 v50, v58, v50
	v_fma_f32 v59, v57, v49, v48
	v_add_f32_e32 v59, v50, v59
	v_and_b32_e32 v48, 0xffff0000, v21
	v_and_b32_e32 v49, 0xffff0000, v25
	v_and_b32_e32 v50, 0xffff0000, v29
	v_mul_f32_e32 v48, v56, v48
	v_mul_f32_e32 v50, v58, v50
	v_fma_f32 v60, v57, v49, v48
	v_add_f32_e32 v60, v50, v60
	v_cvt_pk_bf16_f32 v53, v59, v60
	v_lshlrev_b32_e32 v48, 16, v22
	v_lshlrev_b32_e32 v49, 16, v26
	v_lshlrev_b32_e32 v50, 16, v30
	v_mul_f32_e32 v48, v56, v48
	v_mul_f32_e32 v50, v58, v50
	v_fma_f32 v59, v57, v49, v48
	v_add_f32_e32 v59, v50, v59
	v_and_b32_e32 v48, 0xffff0000, v22
	v_and_b32_e32 v49, 0xffff0000, v26
	v_and_b32_e32 v50, 0xffff0000, v30
	v_mul_f32_e32 v48, v56, v48
	v_mul_f32_e32 v50, v58, v50
	v_fma_f32 v60, v57, v49, v48
	v_add_f32_e32 v60, v50, v60
	v_cvt_pk_bf16_f32 v54, v59, v60
	v_lshlrev_b32_e32 v48, 16, v23
	v_lshlrev_b32_e32 v49, 16, v27
	v_lshlrev_b32_e32 v50, 16, v31
	v_mul_f32_e32 v48, v56, v48
	v_mul_f32_e32 v50, v58, v50
	v_fma_f32 v59, v57, v49, v48
	v_add_f32_e32 v59, v50, v59
	v_and_b32_e32 v48, 0xffff0000, v23
	v_and_b32_e32 v49, 0xffff0000, v27
	v_and_b32_e32 v50, 0xffff0000, v31
	v_mul_f32_e32 v48, v56, v48
	v_mul_f32_e32 v50, v58, v50
	v_fma_f32 v60, v57, v49, v48
	v_add_f32_e32 v60, v50, v60
	v_cvt_pk_bf16_f32 v55, v59, v60
	global_store_dwordx4 v[14:15], v[52:55], off
	v_lshl_add_u64 v[14:15], v[14:15], 0, s[100:101]
	global_load_dword v16, v[6:7], off
	global_load_dword v17, v[6:7], off offset:16
	global_load_dword v18, v[6:7], off offset:32
	global_load_dwordx4 v[20:23], v[8:9], off
	global_load_dwordx4 v[24:27], v[10:11], off
	global_load_dwordx4 v[28:31], v[12:13], off
	v_lshl_add_u64 v[6:7], v[6:7], 0, s[98:99]
	v_lshl_add_u64 v[8:9], v[8:9], 0, s[100:101]
	v_lshl_add_u64 v[10:11], v[10:11], 0, s[100:101]
	v_lshl_add_u64 v[12:13], v[12:13], 0, s[100:101]
	s_waitcnt vmcnt(7)
; __global__ void __launch_bounds__(512, 2) fwd_mega(Args a) {
;     ...
;             const float l0 = LSE[tok * 12 + hs], l1 = LSE[tok * 12 + 4 + hs], l2 = LSE[tok * 12 + 8 + hs];
;             const float mx = fmaxf(l0, fmaxf(l1, l2)); float w0 = __expf(l0 - mx), w1 = __expf(l1 - mx), w2 = __expf(l2 - mx); const float inv = 1.0f / (w0 + w1 + w2); w0 *= inv; w1 *= inv; w2 *= inv;
	v_max3_f32 v48, v32, v33, v34
	v_sub_f32_e32 v49, v32, v48
	v_mul_f32_e32 v49, 0x3fb8aa3b, v49
	v_exp_f32_e32 v49, v49
	v_sub_f32_e32 v50, v33, v48
	v_mul_f32_e32 v50, 0x3fb8aa3b, v50
	v_sub_f32_e32 v51, v34, v48
	v_exp_f32_e32 v50, v50
	v_mul_f32_e32 v51, 0x3fb8aa3b, v51
	v_exp_f32_e32 v51, v51
	v_add_f32_e32 v52, v49, v50
	v_add_f32_e32 v52, v51, v52
	v_div_scale_f32 v53, s[4:5], v52, v52, 1.0
	v_rcp_f32_e32 v54, v53
	s_nop 0
	v_fma_f32 v55, -v53, v54, 1.0
	v_fmac_f32_e32 v54, v55, v54
	v_div_scale_f32 v55, vcc, 1.0, v52, 1.0
	v_mul_f32_e32 v59, v55, v54
	v_fma_f32 v60, -v53, v59, v55
	v_fmac_f32_e32 v59, v60, v54
	v_fma_f32 v53, -v53, v59, v55
	v_div_fmas_f32 v53, v53, v54, v59
	v_div_fixup_f32 v53, v53, v52, 1.0
	v_mul_f32_e32 v57, v50, v53
	v_mul_f32_e32 v58, v51, v53
	v_mul_f32_e32 v56, v49, v53
	v_lshlrev_b32_e32 v48, 16, v36
	v_lshlrev_b32_e32 v49, 16, v40
	v_lshlrev_b32_e32 v50, 16, v44
	v_mul_f32_e32 v48, v56, v48
	v_mul_f32_e32 v50, v58, v50
	v_fma_f32 v59, v57, v49, v48
	v_add_f32_e32 v59, v50, v59
	v_and_b32_e32 v48, 0xffff0000, v36
	v_and_b32_e32 v49, 0xffff0000, v40
	v_and_b32_e32 v50, 0xffff0000, v44
	v_mul_f32_e32 v48, v56, v48
	v_mul_f32_e32 v50, v58, v50
	v_fma_f32 v60, v57, v49, v48
	v_add_f32_e32 v60, v50, v60
	v_cvt_pk_bf16_f32 v52, v59, v60
	v_lshlrev_b32_e32 v48, 16, v37
	v_lshlrev_b32_e32 v49, 16, v41
	v_lshlrev_b32_e32 v50, 16, v45
	v_mul_f32_e32 v48, v56, v48
	v_mul_f32_e32 v50, v58, v50
	v_fma_f32 v59, v57, v49, v48
	v_add_f32_e32 v59, v50, v59
	v_and_b32_e32 v48, 0xffff0000, v37
	v_and_b32_e32 v49, 0xffff0000, v41
	v_and_b32_e32 v50, 0xffff0000, v45
	v_mul_f32_e32 v48, v56, v48
	v_mul_f32_e32 v50, v58, v50
	v_fma_f32 v60, v57, v49, v48
	v_add_f32_e32 v60, v50, v60
	v_cvt_pk_bf16_f32 v53, v59, v60
	v_lshlrev_b32_e32 v48, 16, v38
	v_lshlrev_b32_e32 v49, 16, v42
	v_lshlrev_b32_e32 v50, 16, v46
	v_mul_f32_e32 v48, v56, v48
	v_mul_f32_e32 v50, v58, v50
	v_fma_f32 v59, v57, v49, v48
	v_add_f32_e32 v59, v50, v59
	v_and_b32_e32 v48, 0xffff0000, v38
	v_and_b32_e32 v49, 0xffff0000, v42
	v_and_b32_e32 v50, 0xffff0000, v46
	v_mul_f32_e32 v48, v56, v48
	v_mul_f32_e32 v50, v58, v50
	v_fma_f32 v60, v57, v49, v48
	v_add_f32_e32 v60, v50, v60
	v_cvt_pk_bf16_f32 v54, v59, v60
	v_lshlrev_b32_e32 v48, 16, v39
	v_lshlrev_b32_e32 v49, 16, v43
	v_lshlrev_b32_e32 v50, 16, v47
	v_mul_f32_e32 v48, v56, v48
	v_mul_f32_e32 v50, v58, v50
	v_fma_f32 v59, v57, v49, v48
	v_add_f32_e32 v59, v50, v59
	v_and_b32_e32 v48, 0xffff0000, v39
	v_and_b32_e32 v49, 0xffff0000, v43
	v_and_b32_e32 v50, 0xffff0000, v47
	v_mul_f32_e32 v48, v56, v48
	v_mul_f32_e32 v50, v58, v50
	v_fma_f32 v60, v57, v49, v48
	v_add_f32_e32 v60, v50, v60
	v_cvt_pk_bf16_f32 v55, v59, v60
	global_store_dwordx4 v[14:15], v[52:55], off
	v_lshl_add_u64 v[14:15], v[14:15], 0, s[100:101]
	global_load_dword v32, v[6:7], off
	global_load_dword v33, v[6:7], off offset:16
	global_load_dword v34, v[6:7], off offset:32
	global_load_dwordx4 v[36:39], v[8:9], off
	global_load_dwordx4 v[40:43], v[10:11], off
	global_load_dwordx4 v[44:47], v[12:13], off
	v_lshl_add_u64 v[6:7], v[6:7], 0, s[98:99]
	v_lshl_add_u64 v[8:9], v[8:9], 0, s[100:101]
	v_lshl_add_u64 v[10:11], v[10:11], 0, s[100:101]
	v_lshl_add_u64 v[12:13], v[12:13], 0, s[100:101]
	s_waitcnt vmcnt(7)
	v_max3_f32 v48, v16, v17, v18
	v_sub_f32_e32 v49, v16, v48
	v_mul_f32_e32 v49, 0x3fb8aa3b, v49
	v_exp_f32_e32 v49, v49
	v_sub_f32_e32 v50, v17, v48
	v_mul_f32_e32 v50, 0x3fb8aa3b, v50
	v_sub_f32_e32 v51, v18, v48
	v_exp_f32_e32 v50, v50
	v_mul_f32_e32 v51, 0x3fb8aa3b, v51
	v_exp_f32_e32 v51, v51
	v_add_f32_e32 v52, v49, v50
	v_add_f32_e32 v52, v51, v52
	v_div_scale_f32 v53, s[4:5], v52, v52, 1.0
	v_rcp_f32_e32 v54, v53
	s_nop 0
	v_fma_f32 v55, -v53, v54, 1.0
	v_fmac_f32_e32 v54, v55, v54
	v_div_scale_f32 v55, vcc, 1.0, v52, 1.0
	v_mul_f32_e32 v59, v55, v54
	v_fma_f32 v60, -v53, v59, v55
	v_fmac_f32_e32 v59, v60, v54
	v_fma_f32 v53, -v53, v59, v55
	v_div_fmas_f32 v53, v53, v54, v59
	v_div_fixup_f32 v53, v53, v52, 1.0
	v_mul_f32_e32 v57, v50, v53
	v_mul_f32_e32 v58, v51, v53
	v_mul_f32_e32 v56, v49, v53
	v_lshlrev_b32_e32 v48, 16, v20
	v_lshlrev_b32_e32 v49, 16, v24
	v_lshlrev_b32_e32 v50, 16, v28
	v_mul_f32_e32 v48, v56, v48
	v_mul_f32_e32 v50, v58, v50
	v_fma_f32 v59, v57, v49, v48
	v_add_f32_e32 v59, v50, v59
	v_and_b32_e32 v48, 0xffff0000, v20
	v_and_b32_e32 v49, 0xffff0000, v24
	v_and_b32_e32 v50, 0xffff0000, v28
	v_mul_f32_e32 v48, v56, v48
	v_mul_f32_e32 v50, v58, v50
	v_fma_f32 v60, v57, v49, v48
	v_add_f32_e32 v60, v50, v60
	v_cvt_pk_bf16_f32 v52, v59, v60
	v_lshlrev_b32_e32 v48, 16, v21
	v_lshlrev_b32_e32 v49, 16, v25
	v_lshlrev_b32_e32 v50, 16, v29
	v_mul_f32_e32 v48, v56, v48
	v_mul_f32_e32 v50, v58, v50
	v_fma_f32 v59, v57, v49, v48
	v_add_f32_e32 v59, v50, v59
	v_and_b32_e32 v48, 0xffff0000, v21
	v_and_b32_e32 v49, 0xffff0000, v25
	v_and_b32_e32 v50, 0xffff0000, v29
	v_mul_f32_e32 v48, v56, v48
	v_mul_f32_e32 v50, v58, v50
	v_fma_f32 v60, v57, v49, v48
	v_add_f32_e32 v60, v50, v60
	v_cvt_pk_bf16_f32 v53, v59, v60
	v_lshlrev_b32_e32 v48, 16, v22
	v_lshlrev_b32_e32 v49, 16, v26
	v_lshlrev_b32_e32 v50, 16, v30
	v_mul_f32_e32 v48, v56, v48
	v_mul_f32_e32 v50, v58, v50
	v_fma_f32 v59, v57, v49, v48
	v_add_f32_e32 v59, v50, v59
	v_and_b32_e32 v48, 0xffff0000, v22
	v_and_b32_e32 v49, 0xffff0000, v26
	v_and_b32_e32 v50, 0xffff0000, v30
	v_mul_f32_e32 v48, v56, v48
	v_mul_f32_e32 v50, v58, v50
	v_fma_f32 v60, v57, v49, v48
	v_add_f32_e32 v60, v50, v60
	v_cvt_pk_bf16_f32 v54, v59, v60
	v_lshlrev_b32_e32 v48, 16, v23
	v_lshlrev_b32_e32 v49, 16, v27
	v_lshlrev_b32_e32 v50, 16, v31
	v_mul_f32_e32 v48, v56, v48
	v_mul_f32_e32 v50, v58, v50
	v_fma_f32 v59, v57, v49, v48
	v_add_f32_e32 v59, v50, v59
	v_and_b32_e32 v48, 0xffff0000, v23
	v_and_b32_e32 v49, 0xffff0000, v27
	v_and_b32_e32 v50, 0xffff0000, v31
	v_mul_f32_e32 v48, v56, v48
	v_mul_f32_e32 v50, v58, v50
	v_fma_f32 v60, v57, v49, v48
	v_add_f32_e32 v60, v50, v60
	v_cvt_pk_bf16_f32 v55, v59, v60
	global_store_dwordx4 v[14:15], v[52:55], off
	v_lshl_add_u64 v[14:15], v[14:15], 0, s[100:101]
	global_load_dword v16, v[6:7], off
	global_load_dword v17, v[6:7], off offset:16
	global_load_dword v18, v[6:7], off offset:32
	global_load_dwordx4 v[20:23], v[8:9], off
	global_load_dwordx4 v[24:27], v[10:11], off
	global_load_dwordx4 v[28:31], v[12:13], off
	v_lshl_add_u64 v[6:7], v[6:7], 0, s[98:99]
	v_lshl_add_u64 v[8:9], v[8:9], 0, s[100:101]
	v_lshl_add_u64 v[10:11], v[10:11], 0, s[100:101]
	v_lshl_add_u64 v[12:13], v[12:13], 0, s[100:101]
	s_waitcnt vmcnt(7)
; DI float lo_f(unsigned u) { return __uint_as_float(u << 16); }
; DI float hi_f(unsigned u) { return __uint_as_float(u & 0xffff0000u); }
; DI unsigned pk2(float lo, float hi) { return pg8::cvt_pk_bf16(lo, hi); }
; __global__ void __launch_bounds__(512, 2) fwd_mega(Args a) {
;     ...
;             const size_t off = (size_t)tok * 512 + hs * 128 + ch * 8;
;             const v4u o0 = *(const v4u*)(OG + off), o1 = *(const v4u*)(OG + (size_t)TH * 512 + off), o2 = *(const v4u*)(OG + (size_t)2 * TH * 512 + off);
;             v4u r;
;             r.x = pk2(w0 * lo_f(o0.x) + w1 * lo_f(o1.x) + w2 * lo_f(o2.x), w0 * hi_f(o0.x) + w1 * hi_f(o1.x) + w2 * hi_f(o2.x));
;             r.y = pk2(w0 * lo_f(o0.y) + w1 * lo_f(o1.y) + w2 * lo_f(o2.y), w0 * hi_f(o0.y) + w1 * hi_f(o1.y) + w2 * hi_f(o2.y));
;             r.z = pk2(w0 * lo_f(o0.z) + w1 * lo_f(o1.z) + w2 * lo_f(o2.z), w0 * hi_f(o0.z) + w1 * hi_f(o1.z) + w2 * hi_f(o2.z));
;             r.w = pk2(w0 * lo_f(o0.w) + w1 * lo_f(o1.w) + w2 * lo_f(o2.w), w0 * hi_f(o0.w) + w1 * hi_f(o1.w) + w2 * hi_f(o2.w));
;             *(v4u*)(ATT + off) = r;
	v_max3_f32 v48, v32, v33, v34
	v_sub_f32_e32 v49, v32, v48
	v_mul_f32_e32 v49, 0x3fb8aa3b, v49
	v_exp_f32_e32 v49, v49
	v_sub_f32_e32 v50, v33, v48
	v_mul_f32_e32 v50, 0x3fb8aa3b, v50
	v_sub_f32_e32 v51, v34, v48
	v_exp_f32_e32 v50, v50
	v_mul_f32_e32 v51, 0x3fb8aa3b, v51
	v_exp_f32_e32 v51, v51
	v_add_f32_e32 v52, v49, v50
	v_add_f32_e32 v52, v51, v52
	v_div_scale_f32 v53, s[4:5], v52, v52, 1.0
	v_rcp_f32_e32 v54, v53
	s_nop 0
	v_fma_f32 v55, -v53, v54, 1.0
	v_fmac_f32_e32 v54, v55, v54
	v_div_scale_f32 v55, vcc, 1.0, v52, 1.0
	v_mul_f32_e32 v59, v55, v54
	v_fma_f32 v60, -v53, v59, v55
	v_fmac_f32_e32 v59, v60, v54
	v_fma_f32 v53, -v53, v59, v55
	v_div_fmas_f32 v53, v53, v54, v59
	v_div_fixup_f32 v53, v53, v52, 1.0
	v_mul_f32_e32 v57, v50, v53
	v_mul_f32_e32 v58, v51, v53
	v_mul_f32_e32 v56, v49, v53
	v_lshlrev_b32_e32 v48, 16, v36
	v_lshlrev_b32_e32 v49, 16, v40
	v_lshlrev_b32_e32 v50, 16, v44
	v_mul_f32_e32 v48, v56, v48
	v_mul_f32_e32 v50, v58, v50
	v_fma_f32 v59, v57, v49, v48
	v_add_f32_e32 v59, v50, v59
	v_and_b32_e32 v48, 0xffff0000, v36
	v_and_b32_e32 v49, 0xffff0000, v40
	v_and_b32_e32 v50, 0xffff0000, v44
	v_mul_f32_e32 v48, v56, v48
	v_mul_f32_e32 v50, v58, v50
	v_fma_f32 v60, v57, v49, v48
	v_add_f32_e32 v60, v50, v60
	v_cvt_pk_bf16_f32 v52, v59, v60
	v_lshlrev_b32_e32 v48, 16, v37
	v_lshlrev_b32_e32 v49, 16, v41
	v_lshlrev_b32_e32 v50, 16, v45
	v_mul_f32_e32 v48, v56, v48
	v_mul_f32_e32 v50, v58, v50
	v_fma_f32 v59, v57, v49, v48
	v_add_f32_e32 v59, v50, v59
	v_and_b32_e32 v48, 0xffff0000, v37
	v_and_b32_e32 v49, 0xffff0000, v41
	v_and_b32_e32 v50, 0xffff0000, v45
	v_mul_f32_e32 v48, v56, v48
	v_mul_f32_e32 v50, v58, v50
	v_fma_f32 v60, v57, v49, v48
	v_add_f32_e32 v60, v50, v60
	v_cvt_pk_bf16_f32 v53, v59, v60
	v_lshlrev_b32_e32 v48, 16, v38
	v_lshlrev_b32_e32 v49, 16, v42
	v_lshlrev_b32_e32 v50, 16, v46
	v_mul_f32_e32 v48, v56, v48
	v_mul_f32_e32 v50, v58, v50
	v_fma_f32 v59, v57, v49, v48
	v_add_f32_e32 v59, v50, v59
	v_and_b32_e32 v48, 0xffff0000, v38
	v_and_b32_e32 v49, 0xffff0000, v42
	v_and_b32_e32 v50, 0xffff0000, v46
	v_mul_f32_e32 v48, v56, v48
	v_mul_f32_e32 v50, v58, v50
	v_fma_f32 v60, v57, v49, v48
	v_add_f32_e32 v60, v50, v60
	v_cvt_pk_bf16_f32 v54, v59, v60
	v_lshlrev_b32_e32 v48, 16, v39
	v_lshlrev_b32_e32 v49, 16, v43
	v_lshlrev_b32_e32 v50, 16, v47
	v_mul_f32_e32 v48, v56, v48
	v_mul_f32_e32 v50, v58, v50
	v_fma_f32 v59, v57, v49, v48
	v_add_f32_e32 v59, v50, v59
	v_and_b32_e32 v48, 0xffff0000, v39
	v_and_b32_e32 v49, 0xffff0000, v43
	v_and_b32_e32 v50, 0xffff0000, v47
	v_mul_f32_e32 v48, v56, v48
	v_mul_f32_e32 v50, v58, v50
	v_fma_f32 v60, v57, v49, v48
	v_add_f32_e32 v60, v50, v60
	v_cvt_pk_bf16_f32 v55, v59, v60
	global_store_dwordx4 v[14:15], v[52:55], off
	v_lshl_add_u64 v[14:15], v[14:15], 0, s[100:101]
	global_load_dword v32, v[6:7], off
	global_load_dword v33, v[6:7], off offset:16
	global_load_dword v34, v[6:7], off offset:32
	global_load_dwordx4 v[36:39], v[8:9], off
	global_load_dwordx4 v[40:43], v[10:11], off
	global_load_dwordx4 v[44:47], v[12:13], off
	v_lshl_add_u64 v[6:7], v[6:7], 0, s[98:99]
	v_lshl_add_u64 v[8:9], v[8:9], 0, s[100:101]
	v_lshl_add_u64 v[10:11], v[10:11], 0, s[100:101]
	v_lshl_add_u64 v[12:13], v[12:13], 0, s[100:101]
	s_waitcnt vmcnt(7)
	v_max3_f32 v48, v16, v17, v18
	v_sub_f32_e32 v49, v16, v48
	v_mul_f32_e32 v49, 0x3fb8aa3b, v49
	v_exp_f32_e32 v49, v49
	v_sub_f32_e32 v50, v17, v48
	v_mul_f32_e32 v50, 0x3fb8aa3b, v50
	v_sub_f32_e32 v51, v18, v48
	v_exp_f32_e32 v50, v50
	v_mul_f32_e32 v51, 0x3fb8aa3b, v51
	v_exp_f32_e32 v51, v51
	v_add_f32_e32 v52, v49, v50
	v_add_f32_e32 v52, v51, v52
	v_div_scale_f32 v53, s[4:5], v52, v52, 1.0
	v_rcp_f32_e32 v54, v53
	s_nop 0
	v_fma_f32 v55, -v53, v54, 1.0
	v_fmac_f32_e32 v54, v55, v54
	v_div_scale_f32 v55, vcc, 1.0, v52, 1.0
	v_mul_f32_e32 v59, v55, v54
	v_fma_f32 v60, -v53, v59, v55
	v_fmac_f32_e32 v59, v60, v54
	v_fma_f32 v53, -v53, v59, v55
	v_div_fmas_f32 v53, v53, v54, v59
	v_div_fixup_f32 v53, v53, v52, 1.0
	v_mul_f32_e32 v57, v50, v53
	v_mul_f32_e32 v58, v51, v53
	v_mul_f32_e32 v56, v49, v53
	v_lshlrev_b32_e32 v48, 16, v20
	v_lshlrev_b32_e32 v49, 16, v24
	v_lshlrev_b32_e32 v50, 16, v28
	v_mul_f32_e32 v48, v56, v48
	v_mul_f32_e32 v50, v58, v50
	v_fma_f32 v59, v57, v49, v48
	v_add_f32_e32 v59, v50, v59
	v_and_b32_e32 v48, 0xffff0000, v20
	v_and_b32_e32 v49, 0xffff0000, v24
	v_and_b32_e32 v50, 0xffff0000, v28
	v_mul_f32_e32 v48, v56, v48
	v_mul_f32_e32 v50, v58, v50
	v_fma_f32 v60, v57, v49, v48
	v_add_f32_e32 v60, v50, v60
	v_cvt_pk_bf16_f32 v52, v59, v60
	v_lshlrev_b32_e32 v48, 16, v21
	v_lshlrev_b32_e32 v49, 16, v25
	v_lshlrev_b32_e32 v50, 16, v29
	v_mul_f32_e32 v48, v56, v48
	v_mul_f32_e32 v50, v58, v50
	v_fma_f32 v59, v57, v49, v48
	v_add_f32_e32 v59, v50, v59
	v_and_b32_e32 v48, 0xffff0000, v21
	v_and_b32_e32 v49, 0xffff0000, v25
	v_and_b32_e32 v50, 0xffff0000, v29
	v_mul_f32_e32 v48, v56, v48
	v_mul_f32_e32 v50, v58, v50
	v_fma_f32 v60, v57, v49, v48
	v_add_f32_e32 v60, v50, v60
	v_cvt_pk_bf16_f32 v53, v59, v60
	v_lshlrev_b32_e32 v48, 16, v22
	v_lshlrev_b32_e32 v49, 16, v26
	v_lshlrev_b32_e32 v50, 16, v30
	v_mul_f32_e32 v48, v56, v48
	v_mul_f32_e32 v50, v58, v50
	v_fma_f32 v59, v57, v49, v48
	v_add_f32_e32 v59, v50, v59
	v_and_b32_e32 v48, 0xffff0000, v22
	v_and_b32_e32 v49, 0xffff0000, v26
	v_and_b32_e32 v50, 0xffff0000, v30
	v_mul_f32_e32 v48, v56, v48
	v_mul_f32_e32 v50, v58, v50
	v_fma_f32 v60, v57, v49, v48
	v_add_f32_e32 v60, v50, v60
	v_cvt_pk_bf16_f32 v54, v59, v60
	v_lshlrev_b32_e32 v48, 16, v23
	v_lshlrev_b32_e32 v49, 16, v27
	v_lshlrev_b32_e32 v50, 16, v31
	v_mul_f32_e32 v48, v56, v48
	v_mul_f32_e32 v50, v58, v50
	v_fma_f32 v59, v57, v49, v48
	v_add_f32_e32 v59, v50, v59
	v_and_b32_e32 v48, 0xffff0000, v23
	v_and_b32_e32 v49, 0xffff0000, v27
	v_and_b32_e32 v50, 0xffff0000, v31
	v_mul_f32_e32 v48, v56, v48
	v_mul_f32_e32 v50, v58, v50
	v_fma_f32 v60, v57, v49, v48
	v_add_f32_e32 v60, v50, v60
	v_cvt_pk_bf16_f32 v55, v59, v60
	global_store_dwordx4 v[14:15], v[52:55], off
	v_lshl_add_u64 v[14:15], v[14:15], 0, s[100:101]
	global_load_dword v16, v[6:7], off
	global_load_dword v17, v[6:7], off offset:16
	global_load_dword v18, v[6:7], off offset:32
	global_load_dwordx4 v[20:23], v[8:9], off
	global_load_dwordx4 v[24:27], v[10:11], off
	global_load_dwordx4 v[28:31], v[12:13], off
	v_lshl_add_u64 v[6:7], v[6:7], 0, s[98:99]
	v_lshl_add_u64 v[8:9], v[8:9], 0, s[100:101]
	v_lshl_add_u64 v[10:11], v[10:11], 0, s[100:101]
	v_lshl_add_u64 v[12:13], v[12:13], 0, s[100:101]
	s_waitcnt vmcnt(7)
; DI float lo_f(unsigned u) { return __uint_as_float(u << 16); }
; DI float hi_f(unsigned u) { return __uint_as_float(u & 0xffff0000u); }
; DI unsigned pk2(float lo, float hi) { return pg8::cvt_pk_bf16(lo, hi); }
; __global__ void __launch_bounds__(512, 2) fwd_mega(Args a) {
;     ...
;             v4u r;
;             r.x = pk2(w0 * lo_f(o0.x) + w1 * lo_f(o1.x) + w2 * lo_f(o2.x), w0 * hi_f(o0.x) + w1 * hi_f(o1.x) + w2 * hi_f(o2.x));
;             r.y = pk2(w0 * lo_f(o0.y) + w1 * lo_f(o1.y) + w2 * lo_f(o2.y), w0 * hi_f(o0.y) + w1 * hi_f(o1.y) + w2 * hi_f(o2.y));
;             r.z = pk2(w0 * lo_f(o0.z) + w1 * lo_f(o1.z) + w2 * lo_f(o2.z), w0 * hi_f(o0.z) + w1 * hi_f(o1.z) + w2 * hi_f(o2.z));
;             r.w = pk2(w0 * lo_f(o0.w) + w1 * lo_f(o1.w) + w2 * lo_f(o2.w), w0 * hi_f(o0.w) + w1 * hi_f(o1.w) + w2 * hi_f(o2.w));
;             *(v4u*)(ATT + off) = r;
	v_max3_f32 v48, v32, v33, v34
	v_sub_f32_e32 v49, v32, v48
	v_mul_f32_e32 v49, 0x3fb8aa3b, v49
	v_exp_f32_e32 v49, v49
	v_sub_f32_e32 v50, v33, v48
	v_mul_f32_e32 v50, 0x3fb8aa3b, v50
	v_sub_f32_e32 v51, v34, v48
	v_exp_f32_e32 v50, v50
	v_mul_f32_e32 v51, 0x3fb8aa3b, v51
	v_exp_f32_e32 v51, v51
	v_add_f32_e32 v52, v49, v50
	v_add_f32_e32 v52, v51, v52
	v_div_scale_f32 v53, s[4:5], v52, v52, 1.0
	v_rcp_f32_e32 v54, v53
	s_nop 0
	v_fma_f32 v55, -v53, v54, 1.0
	v_fmac_f32_e32 v54, v55, v54
	v_div_scale_f32 v55, vcc, 1.0, v52, 1.0
	v_mul_f32_e32 v59, v55, v54
	v_fma_f32 v60, -v53, v59, v55
	v_fmac_f32_e32 v59, v60, v54
	v_fma_f32 v53, -v53, v59, v55
	v_div_fmas_f32 v53, v53, v54, v59
	v_div_fixup_f32 v53, v53, v52, 1.0
	v_mul_f32_e32 v57, v50, v53
	v_mul_f32_e32 v58, v51, v53
	v_mul_f32_e32 v56, v49, v53
	v_lshlrev_b32_e32 v48, 16, v36
	v_lshlrev_b32_e32 v49, 16, v40
	v_lshlrev_b32_e32 v50, 16, v44
	v_mul_f32_e32 v48, v56, v48
	v_mul_f32_e32 v50, v58, v50
	v_fma_f32 v59, v57, v49, v48
	v_add_f32_e32 v59, v50, v59
	v_and_b32_e32 v48, 0xffff0000, v36
	v_and_b32_e32 v49, 0xffff0000, v40
	v_and_b32_e32 v50, 0xffff0000, v44
	v_mul_f32_e32 v48, v56, v48
	v_mul_f32_e32 v50, v58, v50
	v_fma_f32 v60, v57, v49, v48
	v_add_f32_e32 v60, v50, v60
	v_cvt_pk_bf16_f32 v52, v59, v60
	v_lshlrev_b32_e32 v48, 16, v37
	v_lshlrev_b32_e32 v49, 16, v41
	v_lshlrev_b32_e32 v50, 16, v45
	v_mul_f32_e32 v48, v56, v48
	v_mul_f32_e32 v50, v58, v50
	v_fma_f32 v59, v57, v49, v48
	v_add_f32_e32 v59, v50, v59
	v_and_b32_e32 v48, 0xffff0000, v37
	v_and_b32_e32 v49, 0xffff0000, v41
	v_and_b32_e32 v50, 0xffff0000, v45
	v_mul_f32_e32 v48, v56, v48
	v_mul_f32_e32 v50, v58, v50
	v_fma_f32 v60, v57, v49, v48
	v_add_f32_e32 v60, v50, v60
	v_cvt_pk_bf16_f32 v53, v59, v60
	v_lshlrev_b32_e32 v48, 16, v38
	v_lshlrev_b32_e32 v49, 16, v42
	v_lshlrev_b32_e32 v50, 16, v46
	v_mul_f32_e32 v48, v56, v48
	v_mul_f32_e32 v50, v58, v50
	v_fma_f32 v59, v57, v49, v48
	v_add_f32_e32 v59, v50, v59
	v_and_b32_e32 v48, 0xffff0000, v38
	v_and_b32_e32 v49, 0xffff0000, v42
	v_and_b32_e32 v50, 0xffff0000, v46
	v_mul_f32_e32 v48, v56, v48
	v_mul_f32_e32 v50, v58, v50
	v_fma_f32 v60, v57, v49, v48
	v_add_f32_e32 v60, v50, v60
	v_cvt_pk_bf16_f32 v54, v59, v60
	v_lshlrev_b32_e32 v48, 16, v39
	v_lshlrev_b32_e32 v49, 16, v43
	v_lshlrev_b32_e32 v50, 16, v47
	v_mul_f32_e32 v48, v56, v48
	v_mul_f32_e32 v50, v58, v50
	v_fma_f32 v59, v57, v49, v48
	v_add_f32_e32 v59, v50, v59
	v_and_b32_e32 v48, 0xffff0000, v39
	v_and_b32_e32 v49, 0xffff0000, v43
	v_and_b32_e32 v50, 0xffff0000, v47
	v_mul_f32_e32 v48, v56, v48
	v_mul_f32_e32 v50, v58, v50
	v_fma_f32 v60, v57, v49, v48
	v_add_f32_e32 v60, v50, v60
	v_cvt_pk_bf16_f32 v55, v59, v60
	global_store_dwordx4 v[14:15], v[52:55], off
	v_lshl_add_u64 v[14:15], v[14:15], 0, s[100:101]
	global_load_dword v32, v[6:7], off
	global_load_dword v33, v[6:7], off offset:16
	global_load_dword v34, v[6:7], off offset:32
	global_load_dwordx4 v[36:39], v[8:9], off
	global_load_dwordx4 v[40:43], v[10:11], off
	global_load_dwordx4 v[44:47], v[12:13], off
	v_lshl_add_u64 v[6:7], v[6:7], 0, s[98:99]
	v_lshl_add_u64 v[8:9], v[8:9], 0, s[100:101]
	v_lshl_add_u64 v[10:11], v[10:11], 0, s[100:101]
	v_lshl_add_u64 v[12:13], v[12:13], 0, s[100:101]
	s_waitcnt vmcnt(7)
	v_max3_f32 v48, v16, v17, v18
	v_sub_f32_e32 v49, v16, v48
	v_mul_f32_e32 v49, 0x3fb8aa3b, v49
	v_exp_f32_e32 v49, v49
	v_sub_f32_e32 v50, v17, v48
	v_mul_f32_e32 v50, 0x3fb8aa3b, v50
	v_sub_f32_e32 v51, v18, v48
	v_exp_f32_e32 v50, v50
	v_mul_f32_e32 v51, 0x3fb8aa3b, v51
	v_exp_f32_e32 v51, v51
	v_add_f32_e32 v52, v49, v50
	v_add_f32_e32 v52, v51, v52
	v_div_scale_f32 v53, s[4:5], v52, v52, 1.0
	v_rcp_f32_e32 v54, v53
	s_nop 0
	v_fma_f32 v55, -v53, v54, 1.0
	v_fmac_f32_e32 v54, v55, v54
	v_div_scale_f32 v55, vcc, 1.0, v52, 1.0
	v_mul_f32_e32 v59, v55, v54
	v_fma_f32 v60, -v53, v59, v55
	v_fmac_f32_e32 v59, v60, v54
	v_fma_f32 v53, -v53, v59, v55
	v_div_fmas_f32 v53, v53, v54, v59
	v_div_fixup_f32 v53, v53, v52, 1.0
	v_mul_f32_e32 v57, v50, v53
	v_mul_f32_e32 v58, v51, v53
	v_mul_f32_e32 v56, v49, v53
	v_lshlrev_b32_e32 v48, 16, v20
	v_lshlrev_b32_e32 v49, 16, v24
	v_lshlrev_b32_e32 v50, 16, v28
	v_mul_f32_e32 v48, v56, v48
	v_mul_f32_e32 v50, v58, v50
	v_fma_f32 v59, v57, v49, v48
	v_add_f32_e32 v59, v50, v59
	v_and_b32_e32 v48, 0xffff0000, v20
	v_and_b32_e32 v49, 0xffff0000, v24
	v_and_b32_e32 v50, 0xffff0000, v28
	v_mul_f32_e32 v48, v56, v48
	v_mul_f32_e32 v50, v58, v50
	v_fma_f32 v60, v57, v49, v48
	v_add_f32_e32 v60, v50, v60
	v_cvt_pk_bf16_f32 v52, v59, v60
	v_lshlrev_b32_e32 v48, 16, v21
	v_lshlrev_b32_e32 v49, 16, v25
	v_lshlrev_b32_e32 v50, 16, v29
	v_mul_f32_e32 v48, v56, v48
	v_mul_f32_e32 v50, v58, v50
	v_fma_f32 v59, v57, v49, v48
	v_add_f32_e32 v59, v50, v59
	v_and_b32_e32 v48, 0xffff0000, v21
	v_and_b32_e32 v49, 0xffff0000, v25
	v_and_b32_e32 v50, 0xffff0000, v29
	v_mul_f32_e32 v48, v56, v48
	v_mul_f32_e32 v50, v58, v50
	v_fma_f32 v60, v57, v49, v48
	v_add_f32_e32 v60, v50, v60
	v_cvt_pk_bf16_f32 v53, v59, v60
	v_lshlrev_b32_e32 v48, 16, v22
	v_lshlrev_b32_e32 v49, 16, v26
	v_lshlrev_b32_e32 v50, 16, v30
	v_mul_f32_e32 v48, v56, v48
	v_mul_f32_e32 v50, v58, v50
	v_fma_f32 v59, v57, v49, v48
	v_add_f32_e32 v59, v50, v59
	v_and_b32_e32 v48, 0xffff0000, v22
	v_and_b32_e32 v49, 0xffff0000, v26
	v_and_b32_e32 v50, 0xffff0000, v30
	v_mul_f32_e32 v48, v56, v48
	v_mul_f32_e32 v50, v58, v50
	v_fma_f32 v60, v57, v49, v48
	v_add_f32_e32 v60, v50, v60
	v_cvt_pk_bf16_f32 v54, v59, v60
	v_lshlrev_b32_e32 v48, 16, v23
	v_lshlrev_b32_e32 v49, 16, v27
	v_lshlrev_b32_e32 v50, 16, v31
	v_mul_f32_e32 v48, v56, v48
	v_mul_f32_e32 v50, v58, v50
	v_fma_f32 v59, v57, v49, v48
	v_add_f32_e32 v59, v50, v59
	v_and_b32_e32 v48, 0xffff0000, v23
	v_and_b32_e32 v49, 0xffff0000, v27
	v_and_b32_e32 v50, 0xffff0000, v31
	v_mul_f32_e32 v48, v56, v48
	v_mul_f32_e32 v50, v58, v50
	v_fma_f32 v60, v57, v49, v48
	v_add_f32_e32 v60, v50, v60
	v_cvt_pk_bf16_f32 v55, v59, v60
	global_store_dwordx4 v[14:15], v[52:55], off
	v_lshl_add_u64 v[14:15], v[14:15], 0, s[100:101]
	global_load_dword v16, v[6:7], off
	global_load_dword v17, v[6:7], off offset:16
	global_load_dword v18, v[6:7], off offset:32
	global_load_dwordx4 v[20:23], v[8:9], off
	global_load_dwordx4 v[24:27], v[10:11], off
	global_load_dwordx4 v[28:31], v[12:13], off
	v_lshl_add_u64 v[6:7], v[6:7], 0, s[98:99]
	v_lshl_add_u64 v[8:9], v[8:9], 0, s[100:101]
	v_lshl_add_u64 v[10:11], v[10:11], 0, s[100:101]
	v_lshl_add_u64 v[12:13], v[12:13], 0, s[100:101]
	s_waitcnt vmcnt(7)
; DI float lo_f(unsigned u) { return __uint_as_float(u << 16); }
; DI float hi_f(unsigned u) { return __uint_as_float(u & 0xffff0000u); }
; DI unsigned pk2(float lo, float hi) { return pg8::cvt_pk_bf16(lo, hi); }
; __global__ void __launch_bounds__(512, 2) fwd_mega(Args a) {
;     ...
;         for (int i = bx * 512 + tid; i < TH * 64; i += G * 512) {
;             const int tok = i >> 6, rem = i & 63, hs = rem >> 4, ch = rem & 15;
;             const float l0 = LSE[tok * 12 + hs], l1 = LSE[tok * 12 + 4 + hs], l2 = LSE[tok * 12 + 8 + hs];
;             const float mx = fmaxf(l0, fmaxf(l1, l2)); float w0 = __expf(l0 - mx), w1 = __expf(l1 - mx), w2 = __expf(l2 - mx); const float inv = 1.0f / (w0 + w1 + w2); w0 *= inv; w1 *= inv; w2 *= inv;
;             const size_t off = (size_t)tok * 512 + hs * 128 + ch * 8;
;             const v4u o0 = *(const v4u*)(OG + off), o1 = *(const v4u*)(OG + (size_t)TH * 512 + off), o2 = *(const v4u*)(OG + (size_t)2 * TH * 512 + off);
;             v4u r;
;             r.x = pk2(w0 * lo_f(o0.x) + w1 * lo_f(o1.x) + w2 * lo_f(o2.x), w0 * hi_f(o0.x) + w1 * hi_f(o1.x) + w2 * hi_f(o2.x));
;             r.y = pk2(w0 * lo_f(o0.y) + w1 * lo_f(o1.y) + w2 * lo_f(o2.y), w0 * hi_f(o0.y) + w1 * hi_f(o1.y) + w2 * hi_f(o2.y));
;             r.z = pk2(w0 * lo_f(o0.z) + w1 * lo_f(o1.z) + w2 * lo_f(o2.z), w0 * hi_f(o0.z) + w1 * hi_f(o1.z) + w2 * hi_f(o2.z));
;             r.w = pk2(w0 * lo_f(o0.w) + w1 * lo_f(o1.w) + w2 * lo_f(o2.w), w0 * hi_f(o0.w) + w1 * hi_f(o1.w) + w2 * hi_f(o2.w));
;             *(v4u*)(ATT + off) = r;
	v_max3_f32 v48, v32, v33, v34
	v_sub_f32_e32 v49, v32, v48
	v_mul_f32_e32 v49, 0x3fb8aa3b, v49
	v_exp_f32_e32 v49, v49
	v_sub_f32_e32 v50, v33, v48
	v_mul_f32_e32 v50, 0x3fb8aa3b, v50
	v_sub_f32_e32 v51, v34, v48
	v_exp_f32_e32 v50, v50
	v_mul_f32_e32 v51, 0x3fb8aa3b, v51
	v_exp_f32_e32 v51, v51
	v_add_f32_e32 v52, v49, v50
	v_add_f32_e32 v52, v51, v52
	v_div_scale_f32 v53, s[4:5], v52, v52, 1.0
	v_rcp_f32_e32 v54, v53
	s_nop 0
	v_fma_f32 v55, -v53, v54, 1.0
	v_fmac_f32_e32 v54, v55, v54
	v_div_scale_f32 v55, vcc, 1.0, v52, 1.0
	v_mul_f32_e32 v59, v55, v54
	v_fma_f32 v60, -v53, v59, v55
	v_fmac_f32_e32 v59, v60, v54
	v_fma_f32 v53, -v53, v59, v55
	v_div_fmas_f32 v53, v53, v54, v59
	v_div_fixup_f32 v53, v53, v52, 1.0
	v_mul_f32_e32 v57, v50, v53
	v_mul_f32_e32 v58, v51, v53
	v_mul_f32_e32 v56, v49, v53
	v_lshlrev_b32_e32 v48, 16, v36
	v_lshlrev_b32_e32 v49, 16, v40
	v_lshlrev_b32_e32 v50, 16, v44
	v_mul_f32_e32 v48, v56, v48
	v_mul_f32_e32 v50, v58, v50
	v_fma_f32 v59, v57, v49, v48
	v_add_f32_e32 v59, v50, v59
	v_and_b32_e32 v48, 0xffff0000, v36
	v_and_b32_e32 v49, 0xffff0000, v40
	v_and_b32_e32 v50, 0xffff0000, v44
	v_mul_f32_e32 v48, v56, v48
	v_mul_f32_e32 v50, v58, v50
	v_fma_f32 v60, v57, v49, v48
	v_add_f32_e32 v60, v50, v60
	v_cvt_pk_bf16_f32 v52, v59, v60
	v_lshlrev_b32_e32 v48, 16, v37
	v_lshlrev_b32_e32 v49, 16, v41
	v_lshlrev_b32_e32 v50, 16, v45
	v_mul_f32_e32 v48, v56, v48
	v_mul_f32_e32 v50, v58, v50
	v_fma_f32 v59, v57, v49, v48
	v_add_f32_e32 v59, v50, v59
	v_and_b32_e32 v48, 0xffff0000, v37
	v_and_b32_e32 v49, 0xffff0000, v41
	v_and_b32_e32 v50, 0xffff0000, v45
	v_mul_f32_e32 v48, v56, v48
	v_mul_f32_e32 v50, v58, v50
	v_fma_f32 v60, v57, v49, v48
	v_add_f32_e32 v60, v50, v60
	v_cvt_pk_bf16_f32 v53, v59, v60
	v_lshlrev_b32_e32 v48, 16, v38
	v_lshlrev_b32_e32 v49, 16, v42
	v_lshlrev_b32_e32 v50, 16, v46
	v_mul_f32_e32 v48, v56, v48
	v_mul_f32_e32 v50, v58, v50
	v_fma_f32 v59, v57, v49, v48
	v_add_f32_e32 v59, v50, v59
	v_and_b32_e32 v48, 0xffff0000, v38
	v_and_b32_e32 v49, 0xffff0000, v42
	v_and_b32_e32 v50, 0xffff0000, v46
	v_mul_f32_e32 v48, v56, v48
	v_mul_f32_e32 v50, v58, v50
	v_fma_f32 v60, v57, v49, v48
	v_add_f32_e32 v60, v50, v60
	v_cvt_pk_bf16_f32 v54, v59, v60
	v_lshlrev_b32_e32 v48, 16, v39
	v_lshlrev_b32_e32 v49, 16, v43
	v_lshlrev_b32_e32 v50, 16, v47
	v_mul_f32_e32 v48, v56, v48
	v_mul_f32_e32 v50, v58, v50
	v_fma_f32 v59, v57, v49, v48
	v_add_f32_e32 v59, v50, v59
	v_and_b32_e32 v48, 0xffff0000, v39
	v_and_b32_e32 v49, 0xffff0000, v43
	v_and_b32_e32 v50, 0xffff0000, v47
	v_mul_f32_e32 v48, v56, v48
	v_mul_f32_e32 v50, v58, v50
	v_fma_f32 v60, v57, v49, v48
	v_add_f32_e32 v60, v50, v60
	v_cvt_pk_bf16_f32 v55, v59, v60
	global_store_dwordx4 v[14:15], v[52:55], off
	v_lshl_add_u64 v[14:15], v[14:15], 0, s[100:101]
	global_load_dword v32, v[6:7], off
	global_load_dword v33, v[6:7], off offset:16
	global_load_dword v34, v[6:7], off offset:32
	global_load_dwordx4 v[36:39], v[8:9], off
	global_load_dwordx4 v[40:43], v[10:11], off
	global_load_dwordx4 v[44:47], v[12:13], off
	v_lshl_add_u64 v[6:7], v[6:7], 0, s[98:99]
	v_lshl_add_u64 v[8:9], v[8:9], 0, s[100:101]
	v_lshl_add_u64 v[10:11], v[10:11], 0, s[100:101]
	v_lshl_add_u64 v[12:13], v[12:13], 0, s[100:101]
	s_waitcnt vmcnt(7)
	v_max3_f32 v48, v16, v17, v18
	v_sub_f32_e32 v49, v16, v48
	v_mul_f32_e32 v49, 0x3fb8aa3b, v49
	v_exp_f32_e32 v49, v49
	v_sub_f32_e32 v50, v17, v48
	v_mul_f32_e32 v50, 0x3fb8aa3b, v50
	v_sub_f32_e32 v51, v18, v48
	v_exp_f32_e32 v50, v50
	v_mul_f32_e32 v51, 0x3fb8aa3b, v51
	v_exp_f32_e32 v51, v51
	v_add_f32_e32 v52, v49, v50
	v_add_f32_e32 v52, v51, v52
	v_div_scale_f32 v53, s[4:5], v52, v52, 1.0
	v_rcp_f32_e32 v54, v53
	s_nop 0
	v_fma_f32 v55, -v53, v54, 1.0
	v_fmac_f32_e32 v54, v55, v54
	v_div_scale_f32 v55, vcc, 1.0, v52, 1.0
	v_mul_f32_e32 v59, v55, v54
	v_fma_f32 v60, -v53, v59, v55
	v_fmac_f32_e32 v59, v60, v54
	v_fma_f32 v53, -v53, v59, v55
	v_div_fmas_f32 v53, v53, v54, v59
	v_div_fixup_f32 v53, v53, v52, 1.0
	v_mul_f32_e32 v57, v50, v53
	v_mul_f32_e32 v58, v51, v53
	v_mul_f32_e32 v56, v49, v53
	v_lshlrev_b32_e32 v48, 16, v20
	v_lshlrev_b32_e32 v49, 16, v24
	v_lshlrev_b32_e32 v50, 16, v28
	v_mul_f32_e32 v48, v56, v48
	v_mul_f32_e32 v50, v58, v50
	v_fma_f32 v59, v57, v49, v48
	v_add_f32_e32 v59, v50, v59
	v_and_b32_e32 v48, 0xffff0000, v20
	v_and_b32_e32 v49, 0xffff0000, v24
	v_and_b32_e32 v50, 0xffff0000, v28
	v_mul_f32_e32 v48, v56, v48
	v_mul_f32_e32 v50, v58, v50
	v_fma_f32 v60, v57, v49, v48
	v_add_f32_e32 v60, v50, v60
	v_cvt_pk_bf16_f32 v52, v59, v60
	v_lshlrev_b32_e32 v48, 16, v21
	v_lshlrev_b32_e32 v49, 16, v25
	v_lshlrev_b32_e32 v50, 16, v29
	v_mul_f32_e32 v48, v56, v48
	v_mul_f32_e32 v50, v58, v50
	v_fma_f32 v59, v57, v49, v48
	v_add_f32_e32 v59, v50, v59
	v_and_b32_e32 v48, 0xffff0000, v21
	v_and_b32_e32 v49, 0xffff0000, v25
	v_and_b32_e32 v50, 0xffff0000, v29
	v_mul_f32_e32 v48, v56, v48
	v_mul_f32_e32 v50, v58, v50
	v_fma_f32 v60, v57, v49, v48
	v_add_f32_e32 v60, v50, v60
	v_cvt_pk_bf16_f32 v53, v59, v60
	v_lshlrev_b32_e32 v48, 16, v22
	v_lshlrev_b32_e32 v49, 16, v26
	v_lshlrev_b32_e32 v50, 16, v30
	v_mul_f32_e32 v48, v56, v48
	v_mul_f32_e32 v50, v58, v50
	v_fma_f32 v59, v57, v49, v48
	v_add_f32_e32 v59, v50, v59
	v_and_b32_e32 v48, 0xffff0000, v22
	v_and_b32_e32 v49, 0xffff0000, v26
	v_and_b32_e32 v50, 0xffff0000, v30
	v_mul_f32_e32 v48, v56, v48
	v_mul_f32_e32 v50, v58, v50
	v_fma_f32 v60, v57, v49, v48
	v_add_f32_e32 v60, v50, v60
	v_cvt_pk_bf16_f32 v54, v59, v60
	v_lshlrev_b32_e32 v48, 16, v23
	v_lshlrev_b32_e32 v49, 16, v27
	v_lshlrev_b32_e32 v50, 16, v31
	v_mul_f32_e32 v48, v56, v48
	v_mul_f32_e32 v50, v58, v50
	v_fma_f32 v59, v57, v49, v48
	v_add_f32_e32 v59, v50, v59
	v_and_b32_e32 v48, 0xffff0000, v23
	v_and_b32_e32 v49, 0xffff0000, v27
	v_and_b32_e32 v50, 0xffff0000, v31
	v_mul_f32_e32 v48, v56, v48
	v_mul_f32_e32 v50, v58, v50
	v_fma_f32 v60, v57, v49, v48
	v_add_f32_e32 v60, v50, v60
	v_cvt_pk_bf16_f32 v55, v59, v60
	global_store_dwordx4 v[14:15], v[52:55], off
	v_lshl_add_u64 v[14:15], v[14:15], 0, s[100:101]
	global_load_dword v16, v[6:7], off
	global_load_dword v17, v[6:7], off offset:16
	global_load_dword v18, v[6:7], off offset:32
	global_load_dwordx4 v[20:23], v[8:9], off
	global_load_dwordx4 v[24:27], v[10:11], off
	global_load_dwordx4 v[28:31], v[12:13], off
	v_lshl_add_u64 v[6:7], v[6:7], 0, s[98:99]
	v_lshl_add_u64 v[8:9], v[8:9], 0, s[100:101]
	v_lshl_add_u64 v[10:11], v[10:11], 0, s[100:101]
	v_lshl_add_u64 v[12:13], v[12:13], 0, s[100:101]
	s_waitcnt vmcnt(7)
; DI float lo_f(unsigned u) { return __uint_as_float(u << 16); }
; DI float hi_f(unsigned u) { return __uint_as_float(u & 0xffff0000u); }
; DI unsigned pk2(float lo, float hi) { return pg8::cvt_pk_bf16(lo, hi); }
; __global__ void __launch_bounds__(512, 2) fwd_mega(Args a) {
;     ...
;         for (int i = bx * 512 + tid; i < TH * 64; i += G * 512) {
;             const int tok = i >> 6, rem = i & 63, hs = rem >> 4, ch = rem & 15;
;             const float l0 = LSE[tok * 12 + hs], l1 = LSE[tok * 12 + 4 + hs], l2 = LSE[tok * 12 + 8 + hs];
;             const float mx = fmaxf(l0, fmaxf(l1, l2)); float w0 = __expf(l0 - mx), w1 = __expf(l1 - mx), w2 = __expf(l2 - mx); const float inv = 1.0f / (w0 + w1 + w2); w0 *= inv; w1 *= inv; w2 *= inv;
;             const size_t off = (size_t)tok * 512 + hs * 128 + ch * 8;
;             const v4u o0 = *(const v4u*)(OG + off), o1 = *(const v4u*)(OG + (size_t)TH * 512 + off), o2 = *(const v4u*)(OG + (size_t)2 * TH * 512 + off);
;             v4u r;
;             r.x = pk2(w0 * lo_f(o0.x) + w1 * lo_f(o1.x) + w2 * lo_f(o2.x), w0 * hi_f(o0.x) + w1 * hi_f(o1.x) + w2 * hi_f(o2.x));
;             r.y = pk2(w0 * lo_f(o0.y) + w1 * lo_f(o1.y) + w2 * lo_f(o2.y), w0 * hi_f(o0.y) + w1 * hi_f(o1.y) + w2 * hi_f(o2.y));
;             r.z = pk2(w0 * lo_f(o0.z) + w1 * lo_f(o1.z) + w2 * lo_f(o2.z), w0 * hi_f(o0.z) + w1 * hi_f(o1.z) + w2 * hi_f(o2.z));
;             r.w = pk2(w0 * lo_f(o0.w) + w1 * lo_f(o1.w) + w2 * lo_f(o2.w), w0 * hi_f(o0.w) + w1 * hi_f(o1.w) + w2 * hi_f(o2.w));
;             *(v4u*)(ATT + off) = r;
	v_max3_f32 v48, v32, v33, v34
	v_sub_f32_e32 v49, v32, v48
	v_mul_f32_e32 v49, 0x3fb8aa3b, v49
	v_exp_f32_e32 v49, v49
	v_sub_f32_e32 v50, v33, v48
	v_mul_f32_e32 v50, 0x3fb8aa3b, v50
	v_sub_f32_e32 v51, v34, v48
	v_exp_f32_e32 v50, v50
	v_mul_f32_e32 v51, 0x3fb8aa3b, v51
	v_exp_f32_e32 v51, v51
	v_add_f32_e32 v52, v49, v50
	v_add_f32_e32 v52, v51, v52
	v_div_scale_f32 v53, s[4:5], v52, v52, 1.0
	v_rcp_f32_e32 v54, v53
	s_nop 0
	v_fma_f32 v55, -v53, v54, 1.0
	v_fmac_f32_e32 v54, v55, v54
	v_div_scale_f32 v55, vcc, 1.0, v52, 1.0
	v_mul_f32_e32 v59, v55, v54
	v_fma_f32 v60, -v53, v59, v55
	v_fmac_f32_e32 v59, v60, v54
	v_fma_f32 v53, -v53, v59, v55
	v_div_fmas_f32 v53, v53, v54, v59
	v_div_fixup_f32 v53, v53, v52, 1.0
	v_mul_f32_e32 v57, v50, v53
	v_mul_f32_e32 v58, v51, v53
	v_mul_f32_e32 v56, v49, v53
	v_lshlrev_b32_e32 v48, 16, v36
	v_lshlrev_b32_e32 v49, 16, v40
	v_lshlrev_b32_e32 v50, 16, v44
	v_mul_f32_e32 v48, v56, v48
	v_mul_f32_e32 v50, v58, v50
	v_fma_f32 v59, v57, v49, v48
	v_add_f32_e32 v59, v50, v59
	v_and_b32_e32 v48, 0xffff0000, v36
	v_and_b32_e32 v49, 0xffff0000, v40
	v_and_b32_e32 v50, 0xffff0000, v44
	v_mul_f32_e32 v48, v56, v48
	v_mul_f32_e32 v50, v58, v50
	v_fma_f32 v60, v57, v49, v48
	v_add_f32_e32 v60, v50, v60
	v_cvt_pk_bf16_f32 v52, v59, v60
	v_lshlrev_b32_e32 v48, 16, v37
	v_lshlrev_b32_e32 v49, 16, v41
	v_lshlrev_b32_e32 v50, 16, v45
	v_mul_f32_e32 v48, v56, v48
	v_mul_f32_e32 v50, v58, v50
	v_fma_f32 v59, v57, v49, v48
	v_add_f32_e32 v59, v50, v59
	v_and_b32_e32 v48, 0xffff0000, v37
	v_and_b32_e32 v49, 0xffff0000, v41
	v_and_b32_e32 v50, 0xffff0000, v45
	v_mul_f32_e32 v48, v56, v48
	v_mul_f32_e32 v50, v58, v50
	v_fma_f32 v60, v57, v49, v48
	v_add_f32_e32 v60, v50, v60
	v_cvt_pk_bf16_f32 v53, v59, v60
	v_lshlrev_b32_e32 v48, 16, v38
	v_lshlrev_b32_e32 v49, 16, v42
	v_lshlrev_b32_e32 v50, 16, v46
	v_mul_f32_e32 v48, v56, v48
	v_mul_f32_e32 v50, v58, v50
	v_fma_f32 v59, v57, v49, v48
	v_add_f32_e32 v59, v50, v59
	v_and_b32_e32 v48, 0xffff0000, v38
	v_and_b32_e32 v49, 0xffff0000, v42
	v_and_b32_e32 v50, 0xffff0000, v46
	v_mul_f32_e32 v48, v56, v48
	v_mul_f32_e32 v50, v58, v50
	v_fma_f32 v60, v57, v49, v48
	v_add_f32_e32 v60, v50, v60
	v_cvt_pk_bf16_f32 v54, v59, v60
	v_lshlrev_b32_e32 v48, 16, v39
	v_lshlrev_b32_e32 v49, 16, v43
	v_lshlrev_b32_e32 v50, 16, v47
	v_mul_f32_e32 v48, v56, v48
	v_mul_f32_e32 v50, v58, v50
	v_fma_f32 v59, v57, v49, v48
	v_add_f32_e32 v59, v50, v59
	v_and_b32_e32 v48, 0xffff0000, v39
	v_and_b32_e32 v49, 0xffff0000, v43
	v_and_b32_e32 v50, 0xffff0000, v47
	v_mul_f32_e32 v48, v56, v48
	v_mul_f32_e32 v50, v58, v50
	v_fma_f32 v60, v57, v49, v48
	v_add_f32_e32 v60, v50, v60
	v_cvt_pk_bf16_f32 v55, v59, v60
	global_store_dwordx4 v[14:15], v[52:55], off
	v_lshl_add_u64 v[14:15], v[14:15], 0, s[100:101]
	global_load_dword v32, v[6:7], off
	global_load_dword v33, v[6:7], off offset:16
	global_load_dword v34, v[6:7], off offset:32
	global_load_dwordx4 v[36:39], v[8:9], off
	global_load_dwordx4 v[40:43], v[10:11], off
	global_load_dwordx4 v[44:47], v[12:13], off
	s_waitcnt vmcnt(7)
; DI float lo_f(unsigned u) { return __uint_as_float(u << 16); }
; DI float hi_f(unsigned u) { return __uint_as_float(u & 0xffff0000u); }
; DI unsigned pk2(float lo, float hi) { return pg8::cvt_pk_bf16(lo, hi); }
; __global__ void __launch_bounds__(512, 2) fwd_mega(Args a) {
;     ...
;         for (int i = bx * 512 + tid; i < TH * 64; i += G * 512) {
;             const int tok = i >> 6, rem = i & 63, hs = rem >> 4, ch = rem & 15;
;             const float l0 = LSE[tok * 12 + hs], l1 = LSE[tok * 12 + 4 + hs], l2 = LSE[tok * 12 + 8 + hs];
;             const float mx = fmaxf(l0, fmaxf(l1, l2)); float w0 = __expf(l0 - mx), w1 = __expf(l1 - mx), w2 = __expf(l2 - mx); const float inv = 1.0f / (w0 + w1 + w2); w0 *= inv; w1 *= inv; w2 *= inv;
;             const size_t off = (size_t)tok * 512 + hs * 128 + ch * 8;
;             const v4u o0 = *(const v4u*)(OG + off), o1 = *(const v4u*)(OG + (size_t)TH * 512 + off), o2 = *(const v4u*)(OG + (size_t)2 * TH * 512 + off);
;             v4u r;
;             r.x = pk2(w0 * lo_f(o0.x) + w1 * lo_f(o1.x) + w2 * lo_f(o2.x), w0 * hi_f(o0.x) + w1 * hi_f(o1.x) + w2 * hi_f(o2.x));
;             r.y = pk2(w0 * lo_f(o0.y) + w1 * lo_f(o1.y) + w2 * lo_f(o2.y), w0 * hi_f(o0.y) + w1 * hi_f(o1.y) + w2 * hi_f(o2.y));
;             r.z = pk2(w0 * lo_f(o0.z) + w1 * lo_f(o1.z) + w2 * lo_f(o2.z), w0 * hi_f(o0.z) + w1 * hi_f(o1.z) + w2 * hi_f(o2.z));
;             r.w = pk2(w0 * lo_f(o0.w) + w1 * lo_f(o1.w) + w2 * lo_f(o2.w), w0 * hi_f(o0.w) + w1 * hi_f(o1.w) + w2 * hi_f(o2.w));
;             *(v4u*)(ATT + off) = r;
	v_max3_f32 v48, v16, v17, v18
	v_sub_f32_e32 v49, v16, v48
	v_mul_f32_e32 v49, 0x3fb8aa3b, v49
	v_exp_f32_e32 v49, v49
	v_sub_f32_e32 v50, v17, v48
	v_mul_f32_e32 v50, 0x3fb8aa3b, v50
	v_sub_f32_e32 v51, v18, v48
	v_exp_f32_e32 v50, v50
	v_mul_f32_e32 v51, 0x3fb8aa3b, v51
	v_exp_f32_e32 v51, v51
	v_add_f32_e32 v52, v49, v50
	v_add_f32_e32 v52, v51, v52
	v_div_scale_f32 v53, s[4:5], v52, v52, 1.0
	v_rcp_f32_e32 v54, v53
	s_nop 0
	v_fma_f32 v55, -v53, v54, 1.0
	v_fmac_f32_e32 v54, v55, v54
	v_div_scale_f32 v55, vcc, 1.0, v52, 1.0
	v_mul_f32_e32 v59, v55, v54
	v_fma_f32 v60, -v53, v59, v55
	v_fmac_f32_e32 v59, v60, v54
	v_fma_f32 v53, -v53, v59, v55
	v_div_fmas_f32 v53, v53, v54, v59
	v_div_fixup_f32 v53, v53, v52, 1.0
	v_mul_f32_e32 v57, v50, v53
	v_mul_f32_e32 v58, v51, v53
	v_mul_f32_e32 v56, v49, v53
	v_lshlrev_b32_e32 v48, 16, v20
	v_lshlrev_b32_e32 v49, 16, v24
	v_lshlrev_b32_e32 v50, 16, v28
	v_mul_f32_e32 v48, v56, v48
	v_mul_f32_e32 v50, v58, v50
	v_fma_f32 v59, v57, v49, v48
	v_add_f32_e32 v59, v50, v59
	v_and_b32_e32 v48, 0xffff0000, v20
	v_and_b32_e32 v49, 0xffff0000, v24
	v_and_b32_e32 v50, 0xffff0000, v28
	v_mul_f32_e32 v48, v56, v48
	v_mul_f32_e32 v50, v58, v50
	v_fma_f32 v60, v57, v49, v48
	v_add_f32_e32 v60, v50, v60
	v_cvt_pk_bf16_f32 v52, v59, v60
	v_lshlrev_b32_e32 v48, 16, v21
	v_lshlrev_b32_e32 v49, 16, v25
	v_lshlrev_b32_e32 v50, 16, v29
	v_mul_f32_e32 v48, v56, v48
	v_mul_f32_e32 v50, v58, v50
	v_fma_f32 v59, v57, v49, v48
	v_add_f32_e32 v59, v50, v59
	v_and_b32_e32 v48, 0xffff0000, v21
	v_and_b32_e32 v49, 0xffff0000, v25
	v_and_b32_e32 v50, 0xffff0000, v29
	v_mul_f32_e32 v48, v56, v48
	v_mul_f32_e32 v50, v58, v50
	v_fma_f32 v60, v57, v49, v48
	v_add_f32_e32 v60, v50, v60
	v_cvt_pk_bf16_f32 v53, v59, v60
	v_lshlrev_b32_e32 v48, 16, v22
	v_lshlrev_b32_e32 v49, 16, v26
	v_lshlrev_b32_e32 v50, 16, v30
	v_mul_f32_e32 v48, v56, v48
	v_mul_f32_e32 v50, v58, v50
	v_fma_f32 v59, v57, v49, v48
	v_add_f32_e32 v59, v50, v59
	v_and_b32_e32 v48, 0xffff0000, v22
	v_and_b32_e32 v49, 0xffff0000, v26
	v_and_b32_e32 v50, 0xffff0000, v30
	v_mul_f32_e32 v48, v56, v48
	v_mul_f32_e32 v50, v58, v50
	v_fma_f32 v60, v57, v49, v48
	v_add_f32_e32 v60, v50, v60
	v_cvt_pk_bf16_f32 v54, v59, v60
	v_lshlrev_b32_e32 v48, 16, v23
	v_lshlrev_b32_e32 v49, 16, v27
	v_lshlrev_b32_e32 v50, 16, v31
	v_mul_f32_e32 v48, v56, v48
	v_mul_f32_e32 v50, v58, v50
	v_fma_f32 v59, v57, v49, v48
	v_add_f32_e32 v59, v50, v59
	v_and_b32_e32 v48, 0xffff0000, v23
	v_and_b32_e32 v49, 0xffff0000, v27
	v_and_b32_e32 v50, 0xffff0000, v31
	v_mul_f32_e32 v48, v56, v48
	v_mul_f32_e32 v50, v58, v50
	v_fma_f32 v60, v57, v49, v48
	v_add_f32_e32 v60, v50, v60
	v_cvt_pk_bf16_f32 v55, v59, v60
	global_store_dwordx4 v[14:15], v[52:55], off
	v_lshl_add_u64 v[14:15], v[14:15], 0, s[100:101]
	s_waitcnt vmcnt(1)
	v_max3_f32 v48, v32, v33, v34
	v_sub_f32_e32 v49, v32, v48
	v_mul_f32_e32 v49, 0x3fb8aa3b, v49
	v_exp_f32_e32 v49, v49
	v_sub_f32_e32 v50, v33, v48
	v_mul_f32_e32 v50, 0x3fb8aa3b, v50
	v_sub_f32_e32 v51, v34, v48
	v_exp_f32_e32 v50, v50
	v_mul_f32_e32 v51, 0x3fb8aa3b, v51
	v_exp_f32_e32 v51, v51
	v_add_f32_e32 v52, v49, v50
	v_add_f32_e32 v52, v51, v52
	v_div_scale_f32 v53, s[4:5], v52, v52, 1.0
	v_rcp_f32_e32 v54, v53
	s_nop 0
	v_fma_f32 v55, -v53, v54, 1.0
	v_fmac_f32_e32 v54, v55, v54
	v_div_scale_f32 v55, vcc, 1.0, v52, 1.0
	v_mul_f32_e32 v59, v55, v54
	v_fma_f32 v60, -v53, v59, v55
	v_fmac_f32_e32 v59, v60, v54
	v_fma_f32 v53, -v53, v59, v55
	v_div_fmas_f32 v53, v53, v54, v59
	v_div_fixup_f32 v53, v53, v52, 1.0
	v_mul_f32_e32 v57, v50, v53
	v_mul_f32_e32 v58, v51, v53
	v_mul_f32_e32 v56, v49, v53
	v_lshlrev_b32_e32 v48, 16, v36
	v_lshlrev_b32_e32 v49, 16, v40
	v_lshlrev_b32_e32 v50, 16, v44
	v_mul_f32_e32 v48, v56, v48
	v_mul_f32_e32 v50, v58, v50
	v_fma_f32 v59, v57, v49, v48
	v_add_f32_e32 v59, v50, v59
	v_and_b32_e32 v48, 0xffff0000, v36
	v_and_b32_e32 v49, 0xffff0000, v40
	v_and_b32_e32 v50, 0xffff0000, v44
	v_mul_f32_e32 v48, v56, v48
	v_mul_f32_e32 v50, v58, v50
	v_fma_f32 v60, v57, v49, v48
	v_add_f32_e32 v60, v50, v60
	v_cvt_pk_bf16_f32 v52, v59, v60
	v_lshlrev_b32_e32 v48, 16, v37
	v_lshlrev_b32_e32 v49, 16, v41
	v_lshlrev_b32_e32 v50, 16, v45
	v_mul_f32_e32 v48, v56, v48
	v_mul_f32_e32 v50, v58, v50
	v_fma_f32 v59, v57, v49, v48
	v_add_f32_e32 v59, v50, v59
	v_and_b32_e32 v48, 0xffff0000, v37
	v_and_b32_e32 v49, 0xffff0000, v41
	v_and_b32_e32 v50, 0xffff0000, v45
	v_mul_f32_e32 v48, v56, v48
	v_mul_f32_e32 v50, v58, v50
	v_fma_f32 v60, v57, v49, v48
	v_add_f32_e32 v60, v50, v60
	v_cvt_pk_bf16_f32 v53, v59, v60
	v_lshlrev_b32_e32 v48, 16, v38
	v_lshlrev_b32_e32 v49, 16, v42
	v_lshlrev_b32_e32 v50, 16, v46
	v_mul_f32_e32 v48, v56, v48
	v_mul_f32_e32 v50, v58, v50
	v_fma_f32 v59, v57, v49, v48
	v_add_f32_e32 v59, v50, v59
	v_and_b32_e32 v48, 0xffff0000, v38
	v_and_b32_e32 v49, 0xffff0000, v42
	v_and_b32_e32 v50, 0xffff0000, v46
	v_mul_f32_e32 v48, v56, v48
	v_mul_f32_e32 v50, v58, v50
	v_fma_f32 v60, v57, v49, v48
	v_add_f32_e32 v60, v50, v60
	v_cvt_pk_bf16_f32 v54, v59, v60
	v_lshlrev_b32_e32 v48, 16, v39
	v_lshlrev_b32_e32 v49, 16, v43
	v_lshlrev_b32_e32 v50, 16, v47
	v_mul_f32_e32 v48, v56, v48
	v_mul_f32_e32 v50, v58, v50
	v_fma_f32 v59, v57, v49, v48
	v_add_f32_e32 v59, v50, v59
	v_and_b32_e32 v48, 0xffff0000, v39
	v_and_b32_e32 v49, 0xffff0000, v43
	v_and_b32_e32 v50, 0xffff0000, v47
	v_mul_f32_e32 v48, v56, v48
	v_mul_f32_e32 v50, v58, v50
	v_fma_f32 v60, v57, v49, v48
	v_add_f32_e32 v60, v50, v60
	v_cvt_pk_bf16_f32 v55, v59, v60
	global_store_dwordx4 v[14:15], v[52:55], off
